# NSA loops: every ds_read2_b64 V-fragment read replaced by two bank-conflict-free ds_read_b64 (on top of in-place PV accumulation and the LDS-staged phase-H epilogue)
# speedup vs baseline: 1.0348x; 1.0056x over previous
; DI f32x4 mfma16(bf16x8 a, bf16x8 b, f32x4 c) { return __builtin_amdgcn_mfma_f32_16x16x32_bf16(a, b, c, 0, 0, 0); }
; template <int MODE, bool MASKED, class MaskF>
; DI void flash_tile(const u16* sK, const u16* sV, const bf16x8 (&qf)[2][2], f32x4 (&O)[2][4], float (&m)[2], float (&l)[2],
;                    float (&ps)[4][4], MaskF ok, bool sel, int lane) {
;     ...
;     for (int ks = 0; ks < 2; ++ks) kf[kt][ks] = *(const bf16x8*)(sK + (16 * kt + l15) * 72 + ks * 32 + lg * 8);
;   if (MODE == 1) {
; #pragma unroll
;     for (int a = 0; a < 4; ++a)
; #pragma unroll
;       for (int b = 0; b < 4; ++b) ps[a][b] = 0.f;
;   }
;   union PFrag { unsigned u[4]; bf16x8 v; };
;   PFrag pf[2][2];
; #pragma unroll
;   for (int qt = 0; qt < 2; ++qt) {
;     f32x4 s[4];
;     const float sinit = (MODE == 3) ? ((MASKED || sel) ? m[qt] : -1e30f) : 0.f;
; #pragma unroll
;     for (int kt = 0; kt < 4; ++kt) {
;       s[kt] = f32x4{sinit, sinit, sinit, sinit};
; #pragma unroll
;       for (int ks = 0; ks < 2; ++ks) s[kt] = mfma16(kf[kt][ks], qf[qt][ks], s[kt]);
;     }
;     float pr[4][4];
;     if (MODE == 3) {
;       float rs = 0.f;
; #pragma unroll
;       for (int kt = 0; kt < 4; ++kt)
; #pragma unroll
;         for (int i = 0; i < 4; ++i) {
;           float pv = __builtin_amdgcn_exp2f(s[kt][i]);
;           if (MASKED) pv = ok(kt, i) ? pv : 0.f;
;           pr[kt][i] = pv;
;           rs += pv;
;         }
;       l[qt] += rs;
;     } else {
;     float mx = -1e30f;
; #pragma unroll
;     for (int kt = 0; kt < 4; ++kt)
; #pragma unroll
;       for (int i = 0; i < 4; ++i) {
;         if (MASKED) s[kt][i] = ok(kt, i) ? s[kt][i] : -1e30f;
;         mx = fmaxf(mx, s[kt][i]);
;       }
;     if (!MASKED) mx = sel ? mx : -1e30f;
;     if (MODE == 1) {
;       const float mm = m[qt], il = l[qt];
; #pragma unroll
;       for (int kt = 0; kt < 4; ++kt)
; #pragma unroll
;         for (int i = 0; i < 4; ++i) {
;           const float pv = (s[kt][i] > -1e29f) ? __builtin_amdgcn_exp2f(s[kt][i] - mm) * il : 0.f;
;           pr[kt][i] = pv;
;           ps[kt][i] += pv;
;         }
; DI void nsa_item(int wv0, PP p, int item, unsigned char* smem) {
;     ...
;       auto ok = [&](int kt, int ii) { return 16 * (kb * 64 + 16 * kt + 4 * lg + ii) + 31 <= tq; };
.LBB0_805:
	ds_read_b128 v[58:61], v78
	ds_read_b128 v[88:91], v78 offset:64
	v_add_u32_e32 v87, 0xfffffcd0, v77
	ds_read_b128 v[96:99], v78 offset:2304
	ds_read_b128 v[100:103], v78 offset:2368
	ds_read_b128 v[108:111], v78 offset:4608
	ds_read_b128 v[112:115], v78 offset:4672
	s_waitcnt lgkmcnt(5)
	v_mfma_f32_16x16x32_bf16 v[92:95], v[58:61], v[2:5], 0
	ds_read_b128 v[116:119], v79
	ds_read_b128 v[120:123], v79 offset:64
	v_cmp_gt_i32_e32 vcc, v87, v151
	v_add_u32_e32 v124, 0xfffffce0, v77
	s_waitcnt lgkmcnt(6)
	v_mfma_f32_16x16x32_bf16 v[92:95], v[88:91], v[6:9], v[92:95]
	v_cmp_gt_i32_e64 s[2:3], v124, v151
	v_add_u32_e32 v131, 0xfffffdd0, v77
	v_cmp_gt_i32_e64 s[8:9], v131, v151
	v_add_u32_e32 v131, 0xfffffde0, v77
	v_cmp_gt_i32_e64 s[10:11], v131, v151
	s_nop 2
	v_cndmask_b32_e32 v87, v92, v148, vcc
	v_add_u32_e32 v92, 0xfffffcf0, v77
	v_cmp_gt_i32_e64 s[4:5], v92, v151
	v_add_u32_e32 v92, 0xfffffd00, v77
	v_cmp_gt_i32_e64 s[6:7], v92, v151
	v_cndmask_b32_e64 v128, v93, v148, s[2:3]
	v_cndmask_b32_e64 v129, v94, v148, s[4:5]
	v_cndmask_b32_e64 v130, v95, v148, s[6:7]
	s_waitcnt lgkmcnt(1)
	v_mfma_f32_16x16x32_bf16 v[92:95], v[116:119], v[2:5], 0
	v_add_u32_e32 v131, 0xfffffdf0, v77
	v_cmp_gt_i32_e64 s[12:13], v131, v151
	v_add_u32_e32 v131, 0xfffffe00, v77
	s_waitcnt lgkmcnt(0)
	v_mfma_f32_16x16x32_bf16 v[92:95], v[120:123], v[6:9], v[92:95]
	v_cmp_gt_i32_e64 s[14:15], v131, v151
	v_add_u32_e32 v131, 0xfffffed0, v77
	v_cmp_gt_i32_e64 s[16:17], v131, v151
	v_add_u32_e32 v131, 0xfffffee0, v77
	v_cmp_gt_i32_e64 s[18:19], v131, v151
	v_add_u32_e32 v131, 0xfffffef0, v77
	v_cmp_gt_i32_e64 s[20:21], v131, v151
	v_add_u32_e32 v131, 0xffffff00, v77
	v_sub_f32_e32 v132, v87, v80
	v_cmp_gt_i32_e64 s[30:31], v77, v151
	v_cmp_gt_i32_e64 s[22:23], v131, v151
	v_subrev_u32_e32 v131, 48, v77
	v_exp_f32_e32 v132, v132
	v_cndmask_b32_e64 v133, v95, v148, s[30:31]
	v_sub_f32_e32 v95, v128, v80
	v_cmp_gt_i32_e64 s[24:25], v131, v151
	v_subrev_u32_e32 v131, 32, v77
	v_exp_f32_e32 v95, v95
	v_cmp_gt_i32_e64 s[26:27], v131, v151
	v_add_u32_e32 v131, -16, v77
	v_cmp_gt_i32_e64 s[28:29], v131, v151
	v_cmp_lt_f32_e64 s[34:35], s82, v87
	v_mfma_f32_16x16x32_bf16 v[104:107], v[96:99], v[2:5], 0
	v_cndmask_b32_e64 v131, v94, v148, s[28:29]
	v_mul_f32_e32 v94, v82, v132
	v_cndmask_b32_e64 v87, 0, v94, s[34:35]
	v_mul_f32_e32 v94, v82, v95
	v_sub_f32_e32 v95, v129, v80
	v_exp_f32_e32 v95, v95
	v_cmp_lt_f32_e64 s[34:35], s82, v128
	v_mfma_f32_16x16x32_bf16 v[104:107], v[100:103], v[6:9], v[104:107]
	v_cndmask_b32_e64 v92, v92, v148, s[24:25]
	v_cndmask_b32_e64 v128, 0, v94, s[34:35]
	v_mul_f32_e32 v94, v82, v95
	v_sub_f32_e32 v95, v130, v80
	v_exp_f32_e32 v95, v95
	s_nop 2
	v_cndmask_b32_e64 v104, v104, v148, s[8:9]
	v_cmp_lt_f32_e64 s[34:35], s82, v129
	v_cndmask_b32_e64 v105, v105, v148, s[10:11]
	v_cndmask_b32_e64 v106, v106, v148, s[12:13]
	v_cndmask_b32_e64 v129, 0, v94, s[34:35]
	v_mul_f32_e32 v94, v82, v95
	v_sub_f32_e32 v95, v104, v80
	v_exp_f32_e32 v95, v95
	v_cmp_lt_f32_e64 s[34:35], s82, v130
	v_mfma_f32_16x16x32_bf16 v[124:127], v[108:111], v[2:5], 0
	v_cndmask_b32_e64 v107, v107, v148, s[14:15]
	v_cndmask_b32_e64 v130, 0, v94, s[34:35]
	v_mul_f32_e32 v94, v82, v95
	v_sub_f32_e32 v95, v105, v80
	v_exp_f32_e32 v95, v95
	v_cmp_lt_f32_e64 s[34:35], s82, v104
	v_mfma_f32_16x16x32_bf16 v[124:127], v[112:115], v[6:9], v[124:127]
	v_cndmask_b32_e64 v93, v93, v148, s[26:27]
	v_cndmask_b32_e64 v104, 0, v94, s[34:35]
	v_mul_f32_e32 v94, v82, v95
	v_sub_f32_e32 v95, v106, v80
	v_exp_f32_e32 v95, v95
	v_cmp_lt_f32_e64 s[34:35], s82, v105
	s_nop 1
	v_cndmask_b32_e64 v124, v124, v148, s[16:17]
	v_cndmask_b32_e64 v125, v125, v148, s[18:19]
	v_cndmask_b32_e64 v105, 0, v94, s[34:35]
	v_mul_f32_e32 v94, v82, v95
	v_sub_f32_e32 v95, v107, v80
	v_exp_f32_e32 v95, v95
	v_cmp_lt_f32_e64 s[34:35], s82, v106
	v_cndmask_b32_e64 v126, v126, v148, s[20:21]
	v_cndmask_b32_e64 v127, v127, v148, s[22:23]
	v_cndmask_b32_e64 v106, 0, v94, s[34:35]
	v_mul_f32_e32 v94, v82, v95
	v_sub_f32_e32 v95, v124, v80
	v_exp_f32_e32 v95, v95
	v_cmp_lt_f32_e64 s[34:35], s82, v107
	v_mfma_f32_16x16x32_bf16 v[58:61], v[58:61], v[10:13], 0
	v_add_f32_e32 v132, 0, v87
	v_cndmask_b32_e64 v107, 0, v94, s[34:35]
	v_mul_f32_e32 v94, v82, v95
	v_sub_f32_e32 v95, v125, v80
	v_exp_f32_e32 v95, v95
	v_cmp_lt_f32_e64 s[34:35], s82, v124
	v_mfma_f32_16x16x32_bf16 v[58:61], v[88:91], v[14:17], v[58:61]
	v_add_f32_e32 v140, 0, v105
	v_cndmask_b32_e64 v124, 0, v94, s[34:35]
	v_mul_f32_e32 v94, v82, v95
	v_sub_f32_e32 v95, v126, v80
	v_exp_f32_e32 v95, v95
	v_cmp_lt_f32_e64 s[34:35], s82, v125
	v_mfma_f32_16x16x32_bf16 v[88:91], v[96:99], v[10:13], 0
	v_sub_f32_e32 v97, v133, v80
	v_cndmask_b32_e64 v125, 0, v94, s[34:35]
	v_mul_f32_e32 v94, v82, v95
	v_sub_f32_e32 v95, v127, v80
	v_exp_f32_e32 v95, v95
	v_cmp_lt_f32_e64 s[34:35], s82, v126
	v_mfma_f32_16x16x32_bf16 v[88:91], v[100:103], v[14:17], v[88:91]
	v_exp_f32_e32 v97, v97
	v_cndmask_b32_e64 v126, 0, v94, s[34:35]
	v_mul_f32_e32 v94, v82, v95
	v_sub_f32_e32 v95, v92, v80
	v_exp_f32_e32 v95, v95
	v_cmp_lt_f32_e64 s[34:35], s82, v127
	v_mul_f32_e32 v102, v82, v97
	v_cndmask_b32_e32 v103, v58, v148, vcc
	v_cndmask_b32_e64 v127, 0, v94, s[34:35]
	v_mul_f32_e32 v94, v82, v95
	v_sub_f32_e32 v95, v93, v80
	v_exp_f32_e32 v95, v95
	v_cmp_lt_f32_e64 s[34:35], s82, v92
	v_cmp_lt_f32_e32 vcc, s82, v103
	v_add_f32_e32 v141, 0, v106
	v_cndmask_b32_e64 v163, 0, v94, s[34:35]
	v_mul_f32_e32 v92, v82, v95
	v_sub_f32_e32 v94, v131, v80
	v_cmp_lt_f32_e64 s[34:35], s82, v93
	v_exp_f32_e32 v96, v94
	v_add_f32_e32 v142, 0, v107
	v_cndmask_b32_e64 v100, 0, v92, s[34:35]
; template <int MODE, bool MASKED, class MaskF>
; DI void flash_tile(const u16* sK, const u16* sV, const bf16x8 (&qf)[2][2], f32x4 (&O)[2][4], float (&m)[2], float (&l)[2],
;                    float (&ps)[4][4], MaskF ok, bool sel, int lane) {
;     ...
;       const float mm = m[qt], il = l[qt];
; #pragma unroll
;       for (int kt = 0; kt < 4; ++kt)
; #pragma unroll
;         for (int i = 0; i < 4; ++i) {
;           const float pv = (s[kt][i] > -1e29f) ? __builtin_amdgcn_exp2f(s[kt][i] - mm) * il : 0.f;
;           pr[kt][i] = pv;
;           ps[kt][i] += pv;
;         }
;     } else {
;       mx = fmaxf(mx, __shfl_xor(mx, 16));
;       mx = fmaxf(mx, __shfl_xor(mx, 32));
;       const float mnew = fmaxf(m[qt], mx);
;       const float alpha = __builtin_amdgcn_exp2f(m[qt] - mnew);
;       m[qt] = mnew;
;       float rs = 0.f;
;       if (MASKED) {
; #pragma unroll
;         for (int kt = 0; kt < 4; ++kt)
; #pragma unroll
;           for (int i = 0; i < 4; ++i) {
;             const float pv = (s[kt][i] > -1e29f) ? __builtin_amdgcn_exp2f(s[kt][i] - mnew) : 0.f;
;             pr[kt][i] = pv;
;             rs += pv;
;           }
;       } else {
;         const float me = sel ? mnew : 1e30f;
; #pragma unroll
;         for (int kt = 0; kt < 4; ++kt)
; #pragma unroll
;           for (int i = 0; i < 4; ++i) {
;             const float pv = __builtin_amdgcn_exp2f(s[kt][i] - me);
;             pr[kt][i] = pv;
;             rs += pv;
;           }
;       }
;       l[qt] = l[qt] * alpha + rs;
;       if (MODE == 2) {
; #pragma unroll
;         for (int dt = 0; dt < 4; ++dt) O[qt][dt] *= alpha;
;       }
;     }
;     }
;     if (MODE != 0) {
; #pragma unroll
;       for (int ks2 = 0; ks2 < 2; ++ks2) {
;         pf[qt][ks2].u[0] = pk2(pr[2 * ks2][0], pr[2 * ks2][1]);
;         pf[qt][ks2].u[1] = pk2(pr[2 * ks2][2], pr[2 * ks2][3]);
;         pf[qt][ks2].u[2] = pk2(pr[2 * ks2 + 1][0], pr[2 * ks2 + 1][1]);
;         pf[qt][ks2].u[3] = pk2(pr[2 * ks2 + 1][2], pr[2 * ks2 + 1][3]);
;       }
;     }
;   }
;   if (MODE != 0) {
; #pragma unroll
;     for (int ks2 = 0; ks2 < 2; ++ks2) {
; #pragma unroll
;       for (int dt = 0; dt < 4; ++dt) {
;         union { uint2 h[2]; bf16x8 v; } vf;
;         vf.h[0] = *(const uint2*)(sV + (16 * dt + l15) * 72 + 32 * ks2 + 4 * lg);
;         vf.h[1] = *(const uint2*)(sV + (16 * dt + l15) * 72 + 32 * ks2 + 16 + 4 * lg);
	v_mfma_f32_16x16x32_bf16 v[92:95], v[108:111], v[10:13], 0
	v_mul_f32_e32 v96, v82, v96
	v_cmp_lt_f32_e64 s[34:35], s82, v131
	v_cndmask_b32_e64 v110, v59, v148, s[2:3]
	v_mfma_f32_16x16x32_bf16 v[92:95], v[112:115], v[14:17], v[92:95]
	v_cndmask_b32_e64 v101, 0, v96, s[34:35]
	v_cndmask_b32_e64 v113, v88, v148, s[8:9]
	v_sub_f32_e32 v88, v103, v81
	v_mfma_f32_16x16x32_bf16 v[96:99], v[116:119], v[10:13], 0
	v_cndmask_b32_e64 v111, v60, v148, s[4:5]
	s_nop 2
	v_cndmask_b32_e64 v117, v95, v148, s[22:23]
	v_exp_f32_e32 v95, v88
	v_mfma_f32_16x16x32_bf16 v[96:99], v[120:123], v[14:17], v[96:99]
	v_cvt_pk_bf16_f32 v88, v87, v128
	v_cndmask_b32_e64 v112, v61, v148, s[6:7]
	v_mul_f32_e32 v87, v83, v95
	v_sub_f32_e32 v95, v110, v81
	v_exp_f32_e32 v95, v95
	s_nop 2
	v_cndmask_b32_e64 v118, v96, v148, s[24:25]
	v_sub_f32_e32 v96, v111, v81
	v_exp_f32_e32 v96, v96
	v_cndmask_b32_e32 v87, 0, v87, vcc
	v_mul_f32_e32 v95, v83, v95
	v_cmp_lt_f32_e32 vcc, s82, v110
	v_cndmask_b32_e64 v115, v90, v148, s[12:13]
	v_cvt_pk_bf16_f32 v90, v104, v105
	v_cndmask_b32_e32 v105, 0, v95, vcc
	v_mul_f32_e32 v95, v83, v96
	v_sub_f32_e32 v96, v112, v81
	v_exp_f32_e32 v96, v96
	v_cmp_lt_f32_e32 vcc, s82, v111
	v_cndmask_b32_e64 v114, v89, v148, s[10:11]
	v_cndmask_b32_e64 v116, v91, v148, s[14:15]
	v_cvt_pk_bf16_f32 v91, v106, v107
	v_cndmask_b32_e32 v106, 0, v95, vcc
	v_sub_f32_e32 v95, v113, v81
	v_mul_f32_e32 v96, v83, v96
	v_cmp_lt_f32_e32 vcc, s82, v112
	v_exp_f32_e32 v95, v95
	v_cndmask_b32_e64 v92, v92, v148, s[16:17]
	v_cndmask_b32_e32 v107, 0, v96, vcc
	v_sub_f32_e32 v96, v114, v81
	v_exp_f32_e32 v96, v96
	v_mul_f32_e32 v95, v83, v95
	v_cmp_lt_f32_e32 vcc, s82, v113
	v_cndmask_b32_e64 v93, v93, v148, s[18:19]
	v_mul_f32_e32 v96, v83, v96
	v_cndmask_b32_e32 v110, 0, v95, vcc
	v_sub_f32_e32 v95, v115, v81
	v_cmp_lt_f32_e32 vcc, s82, v114
	v_exp_f32_e32 v95, v95
	v_cndmask_b32_e64 v94, v94, v148, s[20:21]
	v_cndmask_b32_e32 v111, 0, v96, vcc
	v_sub_f32_e32 v96, v116, v81
	v_exp_f32_e32 v96, v96
	v_mul_f32_e32 v95, v83, v95
	v_cmp_lt_f32_e32 vcc, s82, v115
	v_cmp_lt_f32_e64 s[34:35], s82, v133
	v_mul_f32_e32 v96, v83, v96
	v_cndmask_b32_e32 v112, 0, v95, vcc
	v_sub_f32_e32 v95, v92, v81
	v_cmp_lt_f32_e32 vcc, s82, v116
	v_exp_f32_e32 v95, v95
	v_add_f32_e32 v139, 0, v104
	v_cndmask_b32_e32 v113, 0, v96, vcc
	v_sub_f32_e32 v96, v93, v81
	v_exp_f32_e32 v96, v96
	v_cmp_lt_f32_e32 vcc, s82, v92
	v_sub_f32_e32 v92, v94, v81
	v_exp_f32_e32 v92, v92
	v_mul_f32_e32 v95, v83, v95
	v_cndmask_b32_e32 v114, 0, v95, vcc
	v_mul_f32_e32 v95, v83, v96
	v_cmp_lt_f32_e32 vcc, s82, v93
	v_mul_f32_e32 v92, v83, v92
	v_cndmask_b32_e64 v102, 0, v102, s[34:35]
	v_cndmask_b32_e32 v115, 0, v95, vcc
	v_cmp_lt_f32_e32 vcc, s82, v94
	v_add_f32_e32 v104, v132, v87
	v_add_u32_e32 v122, 0x2000, v84
	v_cndmask_b32_e32 v116, 0, v92, vcc
	v_sub_f32_e32 v92, v117, v81
	v_exp_f32_e32 v96, v92
	v_cmp_lt_f32_e32 vcc, s82, v117
	v_sub_f32_e32 v92, v118, v81
	v_add_f32_e32 v165, 0, v100
	v_mul_f32_e32 v96, v83, v96
	v_cndmask_b32_e32 v117, 0, v96, vcc
	v_cvt_pk_bf16_f32 v96, v87, v105
	v_add_u32_e32 v87, 0x2800, v84
	v_add_f32_e32 v108, 0, v101
	v_add_f32_e32 v109, 0, v102
	v_cndmask_b32_e64 v119, v97, v148, s[26:27]
	v_cvt_pk_bf16_f32 v61, v101, v102
	v_cvt_pk_bf16_f32 v60, v163, v100
	v_exp_f32_e32 v97, v92
	ds_read_b64 v[92:93], v122 offset:1024
	ds_read_b64 v[94:95], v122 offset:1056
	ds_read_b64 v[100:101], v87 offset:1280
	ds_read_b64 v[102:103], v87 offset:1312
	v_add_f32_e32 v154, 0, v125
	v_add_f32_e32 v161, 0, v126
	v_cndmask_b32_e64 v120, v98, v148, s[28:29]
	v_cndmask_b32_e64 v121, v99, v148, s[30:31]
	v_cvt_pk_bf16_f32 v58, v124, v125
	v_cvt_pk_bf16_f32 v59, v126, v127
	v_cvt_pk_bf16_f32 v89, v129, v130
	v_mul_f32_e32 v123, v83, v97
	v_cvt_pk_bf16_f32 v97, v106, v107
	v_cvt_pk_bf16_f32 v98, v110, v111
	v_cvt_pk_bf16_f32 v99, v112, v113
	v_add_u32_e32 v125, 0x3000, v84
	v_add_u32_e32 v126, 0x2000, v85
	s_waitcnt lgkmcnt(1)
; DI f32x4 mfma16(bf16x8 a, bf16x8 b, f32x4 c) { return __builtin_amdgcn_mfma_f32_16x16x32_bf16(a, b, c, 0, 0, 0); }
; template <int MODE, bool MASKED, class MaskF>
; DI void flash_tile(const u16* sK, const u16* sV, const bf16x8 (&qf)[2][2], f32x4 (&O)[2][4], float (&m)[2], float (&l)[2],
;                    float (&ps)[4][4], MaskF ok, bool sel, int lane) {
;     ...
;   if (MODE != 0) {
; #pragma unroll
;     for (int ks2 = 0; ks2 < 2; ++ks2) {
; #pragma unroll
;       for (int dt = 0; dt < 4; ++dt) {
;         union { uint2 h[2]; bf16x8 v; } vf;
;         vf.h[0] = *(const uint2*)(sV + (16 * dt + l15) * 72 + 32 * ks2 + 4 * lg);
;         vf.h[1] = *(const uint2*)(sV + (16 * dt + l15) * 72 + 32 * ks2 + 16 + 4 * lg);
;         O[0][dt] = mfma16(vf.v, pf[0][ks2].v, O[0][dt]);
;         O[1][dt] = mfma16(vf.v, pf[1][ks2].v, O[1][dt]);
;       }
;     }
; DI void nsa_item(int wv0, PP p, int item, unsigned char* smem) {
;     ...
; #pragma unroll
;       for (int kt = 0; kt < 4; ++kt) {
;         const int j = kb * 16 + kt * 4 + lg;
;         sImp[qloc * 132 + j] += ps[kt][0] + ps[kt][1] + ps[kt][2] + ps[kt][3];
;       }
;       __syncthreads();
; #pragma unroll
;       for (int kt = 0; kt < 4; ++kt) {
;         const int j1 = kb * 16 + kt * 4 + lg + 1;
;         if (j1 < 128) sImp[qloc * 132 + j1] += ps[kt][3];
;       }
	v_mfma_f32_16x16x32_bf16 v[54:57], v[92:95], v[88:91], v[54:57]
	v_add_f32_e32 v143, 0, v124
	v_sub_f32_e32 v124, v119, v81
	v_exp_f32_e32 v124, v124
	v_mfma_f32_16x16x32_bf16 v[30:33], v[92:95], v[96:99], v[30:33]
	ds_read_b64 v[92:93], v125 offset:1536
	ds_read_b64 v[94:95], v125 offset:1568
	v_cmp_lt_f32_e32 vcc, s82, v118
	v_add_f32_e32 v134, 0, v128
	s_waitcnt lgkmcnt(1)
	v_mfma_f32_16x16x32_bf16 v[50:53], v[100:103], v[88:91], v[50:53]
	v_cndmask_b32_e32 v118, 0, v123, vcc
	v_mul_f32_e32 v123, v83, v124
	v_sub_f32_e32 v124, v120, v81
	v_mfma_f32_16x16x32_bf16 v[26:29], v[100:103], v[96:99], v[26:29]
	ds_read_b64 v[100:101], v126 offset:1024
	ds_read_b64 v[102:103], v126 offset:1056
	v_exp_f32_e32 v124, v124
	v_cmp_lt_f32_e32 vcc, s82, v119
	s_waitcnt lgkmcnt(1)
	v_mfma_f32_16x16x32_bf16 v[22:25], v[92:95], v[96:99], v[22:25]
	v_add_f32_e32 v135, 0, v129
	v_cndmask_b32_e32 v119, 0, v123, vcc
	v_cmp_lt_f32_e32 vcc, s82, v120
	s_waitcnt lgkmcnt(0)
	v_mfma_f32_16x16x32_bf16 v[18:21], v[100:103], v[96:99], v[18:21]
	ds_read_b64 v[96:97], v87 offset:1344
	ds_read_b64 v[98:99], v87 offset:1376
	v_add_f32_e32 v138, 0, v130
	v_add_f32_e32 v87, v142, v113
	v_mfma_f32_16x16x32_bf16 v[46:49], v[92:95], v[88:91], v[46:49]
	v_sub_f32_e32 v93, v121, v81
	v_exp_f32_e32 v93, v93
	v_mul_f32_e32 v92, v83, v124
	v_cndmask_b32_e32 v120, 0, v92, vcc
	v_cmp_lt_f32_e32 vcc, s82, v121
	v_mul_f32_e32 v92, v83, v93
	v_cvt_pk_bf16_f32 v93, v116, v117
	v_cndmask_b32_e32 v121, 0, v92, vcc
	v_cvt_pk_bf16_f32 v92, v114, v115
	v_cvt_pk_bf16_f32 v94, v118, v119
	v_cvt_pk_bf16_f32 v95, v120, v121
	v_mfma_f32_16x16x32_bf16 v[42:45], v[100:103], v[88:91], v[42:45]
	ds_read_b64 v[88:89], v122 offset:1088
	ds_read_b64 v[90:91], v122 offset:1120
	ds_read_b64 v[100:101], v125 offset:1600
	ds_read_b64 v[102:103], v125 offset:1632
	v_add_f32_e32 v164, 0, v163
	s_waitcnt lgkmcnt(2)
	v_mfma_f32_16x16x32_bf16 v[50:53], v[96:99], v[58:61], v[50:53]
	v_add_f32_e32 v162, 0, v127
	v_cmp_gt_u32_e32 vcc, s0, v73
	v_mfma_f32_16x16x32_bf16 v[26:29], v[96:99], v[92:95], v[26:29]
	ds_read_b64 v[96:97], v126 offset:1088
	ds_read_b64 v[98:99], v126 offset:1120
	s_waitcnt lgkmcnt(2)
	v_mfma_f32_16x16x32_bf16 v[54:57], v[88:91], v[58:61], v[54:57]
	s_waitcnt lgkmcnt(1)
	v_mfma_f32_16x16x32_bf16 v[46:49], v[100:103], v[58:61], v[46:49]
	s_waitcnt lgkmcnt(0)
	v_mfma_f32_16x16x32_bf16 v[42:45], v[96:99], v[58:61], v[42:45]
	ds_read2_b32 v[60:61], v86 offset1:4
	v_add_f32_e32 v59, v108, v120
	v_add_f32_e32 v58, v109, v121
	v_mfma_f32_16x16x32_bf16 v[30:33], v[88:91], v[92:95], v[30:33]
	v_add_f32_e32 v90, v134, v105
	v_add_f32_e32 v91, v135, v106
	v_add_f32_e32 v90, v104, v90
	v_add_f32_e32 v89, v138, v107
	v_add_f32_e32 v90, v91, v90
	v_add_f32_e32 v105, v139, v110
	v_add_f32_e32 v106, v140, v111
	v_add_f32_e32 v90, v89, v90
	v_add_f32_e32 v107, v141, v112
	s_waitcnt lgkmcnt(0)
	v_add_f32_e32 v60, v90, v60
	v_add_f32_e32 v90, v105, v106
	v_add_f32_e32 v90, v107, v90
	v_mfma_f32_16x16x32_bf16 v[22:25], v[100:103], v[92:95], v[22:25]
	v_add_f32_e32 v110, v143, v114
	v_add_f32_e32 v111, v154, v115
	v_add_f32_e32 v100, v164, v118
	v_mfma_f32_16x16x32_bf16 v[18:21], v[96:99], v[92:95], v[18:21]
	v_add_f32_e32 v92, v87, v90
	ds_read2_b32 v[90:91], v86 offset0:8 offset1:12
	v_add_f32_e32 v101, v165, v119
	v_add_f32_e32 v61, v92, v61
	v_add_f32_e32 v112, v161, v116
	ds_write2_b32 v86, v60, v61 offset1:4
	v_add_f32_e32 v60, v110, v111
	v_add_f32_e32 v61, v100, v101
	v_add_f32_e32 v88, v162, v117
	v_add_f32_e32 v60, v112, v60
	v_add_f32_e32 v59, v59, v61
	v_add_f32_e32 v60, v88, v60
	v_add_f32_e32 v59, v58, v59
	s_waitcnt lgkmcnt(1)
	v_add_f32_e32 v60, v60, v90
	v_add_f32_e32 v59, v59, v91
	ds_write2_b32 v86, v60, v59 offset0:8 offset1:12
	s_waitcnt lgkmcnt(0)
	s_barrier
	s_and_saveexec_b64 s[2:3], vcc
	s_cbranch_execz .LBB0_807
	ds_read_b32 v59, v86 offset:4
	s_waitcnt lgkmcnt(0)
	v_add_f32_e32 v59, v89, v59
	ds_write_b32 v86, v59 offset:4

; template <int MODE, bool MASKED, class MaskF>
; DI void flash_tile(const u16* sK, const u16* sV, const bf16x8 (&qf)[2][2], f32x4 (&O)[2][4], float (&m)[2], float (&l)[2],
;                    float (&ps)[4][4], MaskF ok, bool sel, int lane) {
;     ...
;   for (int qt = 0; qt < 2; ++qt) {
;     f32x4 s[4];
;     const float sinit = (MODE == 3) ? ((MASKED || sel) ? m[qt] : -1e30f) : 0.f;
; #pragma unroll
;     for (int kt = 0; kt < 4; ++kt) {
;       s[kt] = f32x4{sinit, sinit, sinit, sinit};
; #pragma unroll
;       for (int ks = 0; ks < 2; ++ks) s[kt] = mfma16(kf[kt][ks], qf[qt][ks], s[kt]);
;     }
;     float pr[4][4];
;     if (MODE == 3) {
;       float rs = 0.f;
; #pragma unroll
;       for (int kt = 0; kt < 4; ++kt)
; #pragma unroll
;         for (int i = 0; i < 4; ++i) {
;           float pv = __builtin_amdgcn_exp2f(s[kt][i]);
;           if (MASKED) pv = ok(kt, i) ? pv : 0.f;
;           pr[kt][i] = pv;
;           rs += pv;
;         }
;       l[qt] += rs;
;     } else {
;     float mx = -1e30f;
; #pragma unroll
;     for (int kt = 0; kt < 4; ++kt)
; #pragma unroll
;       for (int i = 0; i < 4; ++i) {
;         if (MASKED) s[kt][i] = ok(kt, i) ? s[kt][i] : -1e30f;
;         mx = fmaxf(mx, s[kt][i]);
;       }
;     if (!MASKED) mx = sel ? mx : -1e30f;
;     if (MODE == 1) {
;       const float mm = m[qt], il = l[qt];
; #pragma unroll
;       for (int kt = 0; kt < 4; ++kt)
; #pragma unroll
;         for (int i = 0; i < 4; ++i) {
;           const float pv = (s[kt][i] > -1e29f) ? __builtin_amdgcn_exp2f(s[kt][i] - mm) * il : 0.f;
;           pr[kt][i] = pv;
;           ps[kt][i] += pv;
;         }
;     } else {
;       mx = fmaxf(mx, __shfl_xor(mx, 16));
;       mx = fmaxf(mx, __shfl_xor(mx, 32));
; DI void nsa_item(int wv0, PP p, int item, unsigned char* smem) {
;     ...
;         if (bit128(wlo, whi, j)) {
;           const bool sel = bit128(mlo, mhi, j);
;           if (j == i) {
;             auto ok = [&](int kt, int ii) { return sel && (16 * kt + 4 * lg + ii) <= qloc; };
;             if (usefix) flash_tile<3, true>(cK, cV, qf, O, m, l, ps, ok, true, lane);
;             else flash_tile<2, true>(cK, cV, qf, O, m, l, ps, ok, true, lane);
;           } else {
;             if (usefix) flash_tile<3, false>(cK, cV, qf, O, m, l, ps, nomask, sel, lane);
;             else flash_tile<2, false>(cK, cV, qf, O, m, l, ps, nomask, sel, lane);
.LBB0_841:
	v_sub_co_u32_e64 v2, s[36:37], s38, 64
	v_lshrrev_b64 v[66:67], s38, v[130:131]
	v_lshrrev_b64 v[68:69], v2, v[134:135]
	v_cndmask_b32_e64 v0, v68, v66, s[36:37]
	v_and_b32_e32 v0, 1, v0
	v_cmp_eq_u64_e32 vcc, 0, v[0:1]
	s_mov_b32 s81, s40
	s_cbranch_vccnz .LBB0_847
	v_lshrrev_b64 v[66:67], s38, v[20:21]
	v_lshrrev_b64 v[2:3], v2, v[22:23]
	v_cndmask_b32_e64 v0, v2, v66, s[36:37]
	s_mul_i32 s39, s80, 0x4800
	v_and_b32_e32 v0, 1, v0
	v_cmp_eq_u64_e64 s[36:37], 0, v[0:1]
	v_add_u32_e32 v0, s39, v165
	v_lshl_add_u32 v2, v28, 1, v0
	ds_read_b128 v[94:97], v2
	ds_read_b128 v[90:93], v2 offset:64
	ds_read_b128 v[86:89], v2 offset:2304
	ds_read_b128 v[82:85], v2 offset:2368
	ds_read_b128 v[78:81], v2 offset:4608
	ds_read_b128 v[74:77], v2 offset:4672
	v_lshl_add_u32 v0, v164, 1, v0
	ds_read_b128 v[70:73], v0
	ds_read_b128 v[66:69], v0 offset:64
	s_add_i32 s74, s39, 32
	s_cmp_lg_u32 s38, s33
	s_mov_b64 s[38:39], -1
	v_lshlrev_b32_e32 v3, 1, v28
	v_lshlrev_b32_e32 v0, 1, v164
	s_cbranch_scc0 .LBB0_844
	s_waitcnt lgkmcnt(7)
	v_mfma_f32_16x16x32_bf16 v[98:101], v[94:97], v[4:7], 0
	s_mov_b64 s[38:39], 0
	s_waitcnt lgkmcnt(5)
	v_mfma_f32_16x16x32_bf16 v[102:105], v[86:89], v[4:7], 0
	v_mfma_f32_16x16x32_bf16 v[98:101], v[90:93], v[8:11], v[98:101]
	s_waitcnt lgkmcnt(3)
	v_mfma_f32_16x16x32_bf16 v[106:109], v[78:81], v[4:7], 0
	v_mfma_f32_16x16x32_bf16 v[102:105], v[82:85], v[8:11], v[102:105]
	s_nop 4
	v_max3_f32 v2, v98, s1, v99
	v_max3_f32 v2, v2, v100, v101
	s_waitcnt lgkmcnt(1)
	v_mfma_f32_16x16x32_bf16 v[110:113], v[70:73], v[4:7], 0
	v_mfma_f32_16x16x32_bf16 v[106:109], v[74:77], v[8:11], v[106:109]
	v_max3_f32 v2, v2, v102, v103
	v_max3_f32 v2, v2, v104, v105
	s_waitcnt lgkmcnt(0)
	v_mfma_f32_16x16x32_bf16 v[110:113], v[66:69], v[8:11], v[110:113]
	v_mfma_f32_16x16x32_bf16 v[174:177], v[70:73], v[12:15], 0
	s_nop 2
	v_max3_f32 v2, v2, v106, v107
	v_max3_f32 v2, v2, v108, v109
	s_nop 1
	v_max3_f32 v2, v2, v110, v111
	v_max3_f32 v2, v2, v112, v113
	v_cndmask_b32_e64 v2, v2, v148, s[36:37]
	ds_bpermute_b32 v114, v144, v2
	v_mfma_f32_16x16x32_bf16 v[174:177], v[66:69], v[16:19], v[174:177]
	s_waitcnt lgkmcnt(0)
	v_max_f32_e32 v114, v114, v114
	v_max_f32_e32 v2, v2, v114
	ds_bpermute_b32 v114, v145, v2
	s_waitcnt lgkmcnt(0)
	v_max3_f32 v2, v167, v2, v114
	v_cndmask_b32_e64 v115, v2, v150, s[36:37]
	v_sub_f32_e32 v98, v98, v115
	v_exp_f32_e32 v122, v98
	v_sub_f32_e32 v99, v99, v115
	v_exp_f32_e32 v99, v99
	v_sub_f32_e32 v100, v100, v115
	v_exp_f32_e32 v100, v100
	v_sub_f32_e32 v101, v101, v115
	v_exp_f32_e32 v101, v101
	v_sub_f32_e32 v102, v102, v115
	v_add_f32_e32 v98, 0, v122
	v_exp_f32_e32 v123, v102
	v_sub_f32_e32 v102, v103, v115
	v_add_f32_e32 v98, v99, v98
	v_exp_f32_e32 v124, v102
	v_sub_f32_e32 v102, v104, v115
	v_add_f32_e32 v98, v100, v98
	v_exp_f32_e32 v125, v102
	v_sub_f32_e32 v102, v105, v115
	v_add_f32_e32 v98, v101, v98
	v_exp_f32_e32 v126, v102
	v_sub_f32_e32 v102, v106, v115
	v_add_f32_e32 v98, v123, v98
	v_exp_f32_e32 v127, v102
	v_sub_f32_e32 v102, v107, v115
	v_add_f32_e32 v98, v124, v98
	v_exp_f32_e32 v128, v102
	v_sub_f32_e32 v102, v108, v115
	v_add_f32_e32 v98, v125, v98
	v_exp_f32_e32 v129, v102
	v_sub_f32_e32 v102, v109, v115
	v_add_f32_e32 v98, v126, v98
	v_exp_f32_e32 v169, v102
	v_sub_f32_e32 v102, v110, v115
	v_add_f32_e32 v98, v127, v98
	v_exp_f32_e32 v170, v102
	v_sub_f32_e32 v102, v111, v115
	v_add_f32_e32 v98, v128, v98
	v_exp_f32_e32 v171, v102
	v_sub_f32_e32 v102, v112, v115
	v_add_f32_e32 v98, v129, v98
	v_exp_f32_e32 v172, v102
	v_sub_f32_e32 v102, v113, v115
	v_add_f32_e32 v98, v169, v98
	v_exp_f32_e32 v173, v102
	v_add_f32_e32 v98, v170, v98
	v_add_f32_e32 v98, v171, v98
	v_sub_f32_e32 v114, v167, v2
	v_add_f32_e32 v98, v172, v98
	v_add_f32_e32 v168, v173, v98
	v_exp_f32_e32 v98, v114
	v_cvt_pk_bf16_f32 v106, v122, v99
	v_cvt_pk_bf16_f32 v108, v123, v124
	v_cvt_pk_bf16_f32 v109, v125, v126
	v_mfma_f32_16x16x32_bf16 v[122:125], v[94:97], v[12:15], 0
	v_fmac_f32_e32 v168, v163, v98
	v_pk_mul_f32 v[120:121], v[60:61], v[98:99] op_sel_hi:[1,0]
	v_pk_mul_f32 v[118:119], v[58:59], v[98:99] op_sel_hi:[1,0]
	v_pk_mul_f32 v[116:117], v[56:57], v[98:99] op_sel_hi:[1,0]
	v_pk_mul_f32 v[114:115], v[54:55], v[98:99] op_sel_hi:[1,0]
	v_pk_mul_f32 v[112:113], v[52:53], v[98:99] op_sel_hi:[1,0]
	v_pk_mul_f32 v[110:111], v[50:51], v[98:99] op_sel_hi:[1,0]
	v_pk_mul_f32 v[104:105], v[48:49], v[98:99] op_sel_hi:[1,0]
	v_pk_mul_f32 v[102:103], v[46:47], v[98:99] op_sel_hi:[1,0]
	v_cvt_pk_bf16_f32 v98, v127, v128
	v_cvt_pk_bf16_f32 v99, v129, v169
	v_mfma_f32_16x16x32_bf16 v[126:129], v[86:89], v[12:15], 0
	v_cvt_pk_bf16_f32 v107, v100, v101
	v_cvt_pk_bf16_f32 v100, v170, v171
	v_cvt_pk_bf16_f32 v101, v172, v173
	v_mfma_f32_16x16x32_bf16 v[122:125], v[90:93], v[16:19], v[122:125]
	v_mfma_f32_16x16x32_bf16 v[170:173], v[78:81], v[12:15], 0
	v_mfma_f32_16x16x32_bf16 v[126:129], v[82:85], v[16:19], v[126:129]
	s_nop 5
	v_max3_f32 v169, v122, s1, v123
	v_max3_f32 v169, v169, v124, v125
	v_mfma_f32_16x16x32_bf16 v[170:173], v[74:77], v[16:19], v[170:173]
	v_max3_f32 v169, v169, v126, v127
	v_max3_f32 v169, v169, v128, v129
	s_nop 5
	v_max3_f32 v169, v169, v170, v171
	v_max3_f32 v169, v169, v172, v173
	v_max3_f32 v169, v169, v174, v175
	v_max3_f32 v169, v169, v176, v177
	v_cndmask_b32_e64 v169, v169, v148, s[36:37]
	ds_bpermute_b32 v178, v144, v169
	s_waitcnt lgkmcnt(0)
	v_max_f32_e32 v178, v178, v178
	v_max_f32_e32 v169, v169, v178
	ds_bpermute_b32 v178, v145, v169
	s_waitcnt lgkmcnt(0)
; DI f32x4 mfma16(bf16x8 a, bf16x8 b, f32x4 c) { return __builtin_amdgcn_mfma_f32_16x16x32_bf16(a, b, c, 0, 0, 0); }
; template <int MODE, bool MASKED, class MaskF>
; DI void flash_tile(const u16* sK, const u16* sV, const bf16x8 (&qf)[2][2], f32x4 (&O)[2][4], float (&m)[2], float (&l)[2],
;                    float (&ps)[4][4], MaskF ok, bool sel, int lane) {
;     ...
;       mx = fmaxf(mx, __shfl_xor(mx, 16));
;       mx = fmaxf(mx, __shfl_xor(mx, 32));
;       const float mnew = fmaxf(m[qt], mx);
;       const float alpha = __builtin_amdgcn_exp2f(m[qt] - mnew);
;       m[qt] = mnew;
;       float rs = 0.f;
;       if (MASKED) {
; #pragma unroll
;         for (int kt = 0; kt < 4; ++kt)
; #pragma unroll
;           for (int i = 0; i < 4; ++i) {
;             const float pv = (s[kt][i] > -1e29f) ? __builtin_amdgcn_exp2f(s[kt][i] - mnew) : 0.f;
;             pr[kt][i] = pv;
;             rs += pv;
;           }
;       } else {
;         const float me = sel ? mnew : 1e30f;
; #pragma unroll
;         for (int kt = 0; kt < 4; ++kt)
; #pragma unroll
;           for (int i = 0; i < 4; ++i) {
;             const float pv = __builtin_amdgcn_exp2f(s[kt][i] - me);
;             pr[kt][i] = pv;
;             rs += pv;
;           }
;       }
;       l[qt] = l[qt] * alpha + rs;
;       if (MODE == 2) {
; #pragma unroll
;         for (int dt = 0; dt < 4; ++dt) O[qt][dt] *= alpha;
;       }
;     }
;     }
;     if (MODE != 0) {
; #pragma unroll
;       for (int ks2 = 0; ks2 < 2; ++ks2) {
;         pf[qt][ks2].u[0] = pk2(pr[2 * ks2][0], pr[2 * ks2][1]);
;         pf[qt][ks2].u[1] = pk2(pr[2 * ks2][2], pr[2 * ks2][3]);
;         pf[qt][ks2].u[2] = pk2(pr[2 * ks2 + 1][0], pr[2 * ks2 + 1][1]);
;         pf[qt][ks2].u[3] = pk2(pr[2 * ks2 + 1][2], pr[2 * ks2 + 1][3]);
;       }
;     }
;   }
;   if (MODE != 0) {
; #pragma unroll
;     for (int ks2 = 0; ks2 < 2; ++ks2) {
; #pragma unroll
;       for (int dt = 0; dt < 4; ++dt) {
;         union { uint2 h[2]; bf16x8 v; } vf;
;         vf.h[0] = *(const uint2*)(sV + (16 * dt + l15) * 72 + 32 * ks2 + 4 * lg);
;         vf.h[1] = *(const uint2*)(sV + (16 * dt + l15) * 72 + 32 * ks2 + 16 + 4 * lg);
;         O[0][dt] = mfma16(vf.v, pf[0][ks2].v, O[0][dt]);
;         O[1][dt] = mfma16(vf.v, pf[1][ks2].v, O[1][dt]);
;       }
;     }
	v_max3_f32 v169, v166, v169, v178
	v_cndmask_b32_e64 v179, v169, v150, s[36:37]
	v_sub_f32_e32 v122, v122, v179
	v_exp_f32_e32 v184, v122
	v_sub_f32_e32 v123, v123, v179
	v_exp_f32_e32 v123, v123
	v_sub_f32_e32 v124, v124, v179
	v_exp_f32_e32 v124, v124
	v_sub_f32_e32 v125, v125, v179
	v_exp_f32_e32 v125, v125
	v_sub_f32_e32 v126, v126, v179
	v_add_f32_e32 v122, 0, v184
	v_exp_f32_e32 v186, v126
	v_sub_f32_e32 v126, v127, v179
	v_add_f32_e32 v122, v123, v122
	v_exp_f32_e32 v187, v126
	v_sub_f32_e32 v126, v128, v179
	v_add_f32_e32 v122, v124, v122
	v_exp_f32_e32 v188, v126
	v_sub_f32_e32 v126, v129, v179
	v_add_f32_e32 v122, v125, v122
	v_exp_f32_e32 v189, v126
	v_sub_f32_e32 v126, v170, v179
	v_add_f32_e32 v122, v186, v122
	v_exp_f32_e32 v190, v126
	v_sub_f32_e32 v126, v171, v179
	v_add_f32_e32 v122, v187, v122
	v_exp_f32_e32 v171, v126
	v_sub_f32_e32 v126, v172, v179
	v_add_f32_e32 v122, v188, v122
	v_exp_f32_e32 v191, v126
	v_sub_f32_e32 v126, v173, v179
	v_add_f32_e32 v122, v189, v122
	v_exp_f32_e32 v192, v126
	v_sub_f32_e32 v126, v174, v179
	v_add_f32_e32 v122, v190, v122
	v_exp_f32_e32 v193, v126
	v_sub_f32_e32 v126, v175, v179
	v_add_f32_e32 v122, v171, v122
	v_exp_f32_e32 v194, v126
	v_sub_f32_e32 v126, v176, v179
	v_add_f32_e32 v122, v191, v122
	v_exp_f32_e32 v195, v126
	v_sub_f32_e32 v126, v177, v179
	v_add_f32_e32 v122, v192, v122
	v_exp_f32_e32 v196, v126
	v_add_f32_e32 v122, v193, v122
	v_add_f32_e32 v122, v194, v122
	v_sub_f32_e32 v178, v166, v169
	v_add_f32_e32 v122, v195, v122
	v_add_f32_e32 v170, v196, v122
	v_exp_f32_e32 v122, v178
	v_cvt_pk_bf16_f32 v184, v184, v123
	v_cvt_pk_bf16_f32 v185, v124, v125
	v_cvt_pk_bf16_f32 v125, v195, v196
	v_fmac_f32_e32 v170, v162, v122
	v_pk_mul_f32 v[128:129], v[44:45], v[122:123] op_sel_hi:[1,0]
	v_pk_mul_f32 v[126:127], v[42:43], v[122:123] op_sel_hi:[1,0]
	v_pk_mul_f32 v[174:175], v[40:41], v[122:123] op_sel_hi:[1,0]
	v_pk_mul_f32 v[172:173], v[38:39], v[122:123] op_sel_hi:[1,0]
	v_pk_mul_f32 v[178:179], v[36:37], v[122:123] op_sel_hi:[1,0]
	v_pk_mul_f32 v[176:177], v[34:35], v[122:123] op_sel_hi:[1,0]
	v_pk_mul_f32 v[182:183], v[32:33], v[122:123] op_sel_hi:[1,0]
	v_pk_mul_f32 v[180:181], v[30:31], v[122:123] op_sel_hi:[1,0]
	v_cvt_pk_bf16_f32 v122, v190, v171
	v_lshlrev_b32_e32 v171, 1, v153
	v_cvt_pk_bf16_f32 v123, v191, v192
	v_add3_u32 v192, s74, v3, v171
	v_add_u32_e32 v196, 0x2000, v192
	v_cvt_pk_bf16_f32 v186, v186, v187
	v_cvt_pk_bf16_f32 v187, v188, v189
	ds_read_b64 v[188:189], v196 offset:1024
	ds_read_b64 v[190:191], v196 offset:1056
	v_add_u32_e32 v197, 0x2800, v192
	s_waitcnt lgkmcnt(0)
	v_mfma_f32_16x16x32_bf16 v[118:121], v[188:191], v[106:109], v[118:121]
	v_add_u32_e32 v198, 0x3000, v192
	v_cvt_pk_bf16_f32 v124, v193, v194
	v_mfma_f32_16x16x32_bf16 v[126:129], v[188:191], v[184:187], v[126:129]
	ds_read_b64 v[188:189], v197 offset:1280
	ds_read_b64 v[190:191], v197 offset:1312
	s_waitcnt lgkmcnt(0)
	v_mfma_f32_16x16x32_bf16 v[114:117], v[188:191], v[106:109], v[114:117]
	v_mfma_f32_16x16x32_bf16 v[172:175], v[188:191], v[184:187], v[172:175]
	ds_read_b64 v[188:189], v198 offset:1536
	ds_read_b64 v[190:191], v198 offset:1568
	s_waitcnt lgkmcnt(0)
	v_mfma_f32_16x16x32_bf16 v[192:195], v[188:191], v[106:109], v[110:113]
	s_nop 2
	v_add3_u32 v110, s74, v0, v171
	v_add_u32_e32 v171, 0x2000, v110
	ds_read_b64 v[110:111], v171 offset:1024
	ds_read_b64 v[112:113], v171 offset:1056
	v_mfma_f32_16x16x32_bf16 v[176:179], v[188:191], v[184:187], v[176:179]
	s_waitcnt lgkmcnt(0)
	v_mfma_f32_16x16x32_bf16 v[188:191], v[110:113], v[106:109], v[102:105]
	ds_read_b64 v[106:107], v196 offset:1088
	ds_read_b64 v[108:109], v196 offset:1120
	s_waitcnt lgkmcnt(0)
	v_mfma_f32_16x16x32_bf16 v[102:105], v[106:109], v[98:101], v[118:121]
	s_nop 2
	ds_read_b64 v[118:119], v197 offset:1344
	ds_read_b64 v[120:121], v197 offset:1376
	v_mfma_f32_16x16x32_bf16 v[180:183], v[110:113], v[184:187], v[180:183]
	v_mfma_f32_16x16x32_bf16 v[106:109], v[106:109], v[122:125], v[126:129]
	s_waitcnt lgkmcnt(0)
	v_mfma_f32_16x16x32_bf16 v[110:113], v[118:121], v[98:101], v[114:117]
	s_nop 0
	ds_read_b64 v[126:127], v198 offset:1600
	ds_read_b64 v[128:129], v198 offset:1632
	v_mfma_f32_16x16x32_bf16 v[114:117], v[118:121], v[122:125], v[172:175]
	s_nop 2
	ds_read_b64 v[172:173], v171 offset:1088
	ds_read_b64 v[174:175], v171 offset:1120
	s_waitcnt lgkmcnt(1)
	v_mfma_f32_16x16x32_bf16 v[118:121], v[126:129], v[98:101], v[192:195]
	v_mfma_f32_16x16x32_bf16 v[126:129], v[126:129], v[122:125], v[176:179]
	s_waitcnt lgkmcnt(0)
	v_mfma_f32_16x16x32_bf16 v[98:101], v[172:175], v[98:101], v[188:191]
	v_mfma_f32_16x16x32_bf16 v[122:125], v[172:175], v[122:125], v[180:183]
; template <int MODE, bool MASKED, class MaskF>
; DI void flash_tile(const u16* sK, const u16* sV, const bf16x8 (&qf)[2][2], f32x4 (&O)[2][4], float (&m)[2], float (&l)[2],
;                    float (&ps)[4][4], MaskF ok, bool sel, int lane) {
;     ...
;     float mx = -1e30f;
; #pragma unroll
;     for (int kt = 0; kt < 4; ++kt)
; #pragma unroll
;       for (int i = 0; i < 4; ++i) {
;         if (MASKED) s[kt][i] = ok(kt, i) ? s[kt][i] : -1e30f;
;         mx = fmaxf(mx, s[kt][i]);
;       }
;     if (!MASKED) mx = sel ? mx : -1e30f;
;     if (MODE == 1) {
;       const float mm = m[qt], il = l[qt];
; #pragma unroll
;       for (int kt = 0; kt < 4; ++kt)
; #pragma unroll
;         for (int i = 0; i < 4; ++i) {
;           const float pv = (s[kt][i] > -1e29f) ? __builtin_amdgcn_exp2f(s[kt][i] - mm) * il : 0.f;
;           pr[kt][i] = pv;
;           ps[kt][i] += pv;
;         }
;     } else {
;       mx = fmaxf(mx, __shfl_xor(mx, 16));
;       mx = fmaxf(mx, __shfl_xor(mx, 32));
;       const float mnew = fmaxf(m[qt], mx);
;       const float alpha = __builtin_amdgcn_exp2f(m[qt] - mnew);
;       m[qt] = mnew;
;       float rs = 0.f;
;       if (MASKED) {
; #pragma unroll
;         for (int kt = 0; kt < 4; ++kt)
; #pragma unroll
;           for (int i = 0; i < 4; ++i) {
;             const float pv = (s[kt][i] > -1e29f) ? __builtin_amdgcn_exp2f(s[kt][i] - mnew) : 0.f;
;             pr[kt][i] = pv;
;             rs += pv;
;           }
; DI void nsa_item(int wv0, PP p, int item, unsigned char* smem) {
;     ...
;           if (j == i) {
;             auto ok = [&](int kt, int ii) { return sel && (16 * kt + 4 * lg + ii) <= qloc; };
;             if (usefix) flash_tile<3, true>(cK, cV, qf, O, m, l, ps, ok, true, lane);
;             else flash_tile<2, true>(cK, cV, qf, O, m, l, ps, ok, true, lane);
.LBB0_844:
	s_andn2_b64 vcc, exec, s[38:39]
	s_cbranch_vccnz .LBB0_846
	s_waitcnt lgkmcnt(7)
	v_mfma_f32_16x16x32_bf16 v[98:101], v[94:97], v[4:7], 0
	s_or_b64 vcc, s[36:37], s[2:3]
	s_or_b64 s[38:39], s[36:37], s[6:7]
	s_or_b64 s[40:41], s[36:37], s[8:9]
	s_waitcnt lgkmcnt(6)
	v_mfma_f32_16x16x32_bf16 v[98:101], v[90:93], v[8:11], v[98:101]
	s_or_b64 s[42:43], s[36:37], s[10:11]
	s_or_b64 s[44:45], s[36:37], s[12:13]
	s_or_b64 s[46:47], s[36:37], s[14:15]
	s_waitcnt lgkmcnt(5)
	v_mfma_f32_16x16x32_bf16 v[102:105], v[86:89], v[4:7], 0
	s_or_b64 s[48:49], s[36:37], s[16:17]
	s_nop 1
	v_cndmask_b32_e32 v106, v98, v148, vcc
	v_cndmask_b32_e64 v2, v148, v99, s[4:5]
	v_cndmask_b32_e64 v108, v100, v148, s[38:39]
	v_cndmask_b32_e64 v109, v101, v148, s[40:41]
	s_waitcnt lgkmcnt(4)
	v_mfma_f32_16x16x32_bf16 v[98:101], v[82:85], v[8:11], v[102:105]
	v_cndmask_b32_e64 v107, v2, v148, s[36:37]
	v_max3_f32 v2, v106, s1, v107
	v_max3_f32 v2, v2, v108, v109
	s_waitcnt lgkmcnt(3)
	v_mfma_f32_16x16x32_bf16 v[102:105], v[78:81], v[4:7], 0
	s_or_b64 s[50:51], s[36:37], s[18:19]
	s_nop 1
	v_cndmask_b32_e64 v110, v98, v148, s[42:43]
	v_cndmask_b32_e64 v111, v99, v148, s[44:45]
	v_cndmask_b32_e64 v112, v100, v148, s[46:47]
	v_cndmask_b32_e64 v113, v101, v148, s[48:49]
	s_waitcnt lgkmcnt(1)
	v_mfma_f32_16x16x32_bf16 v[98:101], v[70:73], v[4:7], 0
	v_max3_f32 v2, v2, v110, v111
	s_or_b64 s[52:53], s[36:37], s[20:21]
	v_max3_f32 v2, v2, v112, v113
	v_mfma_f32_16x16x32_bf16 v[102:105], v[74:77], v[8:11], v[102:105]
	s_or_b64 s[54:55], s[36:37], s[22:23]
	s_or_b64 s[56:57], s[36:37], s[24:25]
	s_or_b64 s[58:59], s[36:37], s[26:27]
	s_waitcnt lgkmcnt(0)
	v_mfma_f32_16x16x32_bf16 v[98:101], v[66:69], v[8:11], v[98:101]
	s_or_b64 s[60:61], s[36:37], s[28:29]
	s_nop 1
	v_cndmask_b32_e64 v102, v102, v148, s[50:51]
	v_cndmask_b32_e64 v103, v103, v148, s[52:53]
	v_max3_f32 v2, v2, v102, v103
	v_cndmask_b32_e64 v104, v104, v148, s[54:55]
	v_cndmask_b32_e64 v105, v105, v148, s[56:57]
	v_max3_f32 v2, v2, v104, v105
	v_cndmask_b32_e64 v98, v98, v148, s[58:59]
	v_cndmask_b32_e64 v99, v99, v148, s[60:61]
	s_or_b64 s[62:63], s[36:37], s[30:31]
	s_or_b64 s[64:65], s[36:37], s[34:35]
	v_max3_f32 v2, v2, v98, v99
	v_cndmask_b32_e64 v100, v100, v148, s[62:63]
	v_cndmask_b32_e64 v101, v101, v148, s[64:65]
	v_max3_f32 v2, v2, v100, v101
	ds_bpermute_b32 v114, v144, v2
	v_cmp_lt_f32_e64 s[66:67], s82, v106
	v_mfma_f32_16x16x32_bf16 v[94:97], v[94:97], v[12:15], 0
	s_waitcnt lgkmcnt(0)
	v_max_f32_e32 v114, v114, v114
	v_max_f32_e32 v2, v2, v114
	ds_bpermute_b32 v114, v145, v2
	v_mfma_f32_16x16x32_bf16 v[90:93], v[90:93], v[16:19], v[94:97]
	s_waitcnt lgkmcnt(0)
	v_max3_f32 v2, v167, v2, v114
	v_sub_f32_e32 v115, v106, v2
	v_exp_f32_e32 v115, v115
	v_sub_f32_e32 v116, v107, v2
	v_exp_f32_e32 v116, v116
	v_sub_f32_e32 v117, v109, v2
	v_cndmask_b32_e64 v106, 0, v115, s[66:67]
	v_cmp_lt_f32_e64 s[66:67], s82, v107
	v_exp_f32_e32 v117, v117
	v_sub_f32_e32 v114, v167, v2
	v_cndmask_b32_e64 v107, 0, v116, s[66:67]
	v_sub_f32_e32 v116, v108, v2
	v_exp_f32_e32 v116, v116
	v_cmp_lt_f32_e64 s[66:67], s82, v108
	v_sub_f32_e32 v94, v101, v2
	v_exp_f32_e32 v97, v94
	v_cndmask_b32_e64 v108, 0, v116, s[66:67]
	v_sub_f32_e32 v116, v110, v2
	v_exp_f32_e32 v116, v116
	v_cmp_lt_f32_e64 s[66:67], s82, v109
	v_exp_f32_e32 v94, v114
	v_mfma_f32_16x16x32_bf16 v[78:81], v[78:81], v[12:15], 0
	v_cndmask_b32_e64 v109, 0, v117, s[66:67]
	v_sub_f32_e32 v117, v111, v2
	v_cmp_lt_f32_e64 s[66:67], s82, v110
	v_exp_f32_e32 v117, v117
	v_mfma_f32_16x16x32_bf16 v[70:73], v[70:73], v[12:15], 0
	v_cndmask_b32_e64 v110, 0, v116, s[66:67]
	v_sub_f32_e32 v116, v112, v2
	v_exp_f32_e32 v116, v116
	v_cmp_lt_f32_e64 s[66:67], s82, v111
	v_mfma_f32_16x16x32_bf16 v[86:89], v[86:89], v[12:15], 0
	v_add_f32_e32 v115, 0, v106
	v_cndmask_b32_e64 v111, 0, v117, s[66:67]
	v_sub_f32_e32 v117, v113, v2
	v_cmp_lt_f32_e64 s[66:67], s82, v112
	v_exp_f32_e32 v117, v117
	v_mfma_f32_16x16x32_bf16 v[74:77], v[74:77], v[16:19], v[78:81]
	v_cndmask_b32_e64 v112, 0, v116, s[66:67]
	v_sub_f32_e32 v116, v102, v2
	v_exp_f32_e32 v116, v116
	v_cmp_lt_f32_e64 s[66:67], s82, v113
	v_mfma_f32_16x16x32_bf16 v[82:85], v[82:85], v[16:19], v[86:89]
	v_add_f32_e32 v115, v107, v115
	v_cndmask_b32_e64 v113, 0, v117, s[66:67]
	v_sub_f32_e32 v117, v103, v2
	v_cmp_lt_f32_e64 s[66:67], s82, v102
	v_exp_f32_e32 v117, v117
	v_add_f32_e32 v115, v108, v115
	v_cndmask_b32_e64 v102, 0, v116, s[66:67]
	v_sub_f32_e32 v116, v104, v2
	v_exp_f32_e32 v116, v116
	v_cmp_lt_f32_e64 s[66:67], s82, v103
	v_cndmask_b32_e64 v82, v82, v148, s[42:43]
	v_cndmask_b32_e64 v83, v83, v148, s[44:45]
	v_cndmask_b32_e64 v103, 0, v117, s[66:67]
	v_sub_f32_e32 v117, v105, v2
	v_cmp_lt_f32_e64 s[66:67], s82, v104
	v_exp_f32_e32 v117, v117
	v_add_f32_e32 v115, v109, v115
	v_cndmask_b32_e64 v104, 0, v116, s[66:67]
	v_sub_f32_e32 v116, v98, v2
	v_exp_f32_e32 v116, v116
	v_cmp_lt_f32_e64 s[66:67], s82, v105
	v_cndmask_b32_e64 v84, v84, v148, s[46:47]
	v_cndmask_b32_e64 v85, v85, v148, s[48:49]
	v_cndmask_b32_e64 v105, 0, v117, s[66:67]
	v_sub_f32_e32 v117, v99, v2
	v_cmp_lt_f32_e64 s[66:67], s82, v98
	v_exp_f32_e32 v117, v117
	v_add_f32_e32 v115, v110, v115
	v_cndmask_b32_e64 v98, 0, v116, s[66:67]
	v_sub_f32_e32 v116, v100, v2
	v_exp_f32_e32 v116, v116
	v_cmp_lt_f32_e64 s[66:67], s82, v99
	v_cndmask_b32_e64 v74, v74, v148, s[50:51]
	v_cndmask_b32_e64 v75, v75, v148, s[52:53]
	v_cndmask_b32_e64 v99, 0, v117, s[66:67]
	v_cmp_lt_f32_e64 s[66:67], s82, v100
	v_add_f32_e32 v115, v111, v115
	v_cndmask_b32_e64 v76, v76, v148, s[54:55]
	v_cndmask_b32_e64 v95, 0, v116, s[66:67]
; DI f32x4 mfma16(bf16x8 a, bf16x8 b, f32x4 c) { return __builtin_amdgcn_mfma_f32_16x16x32_bf16(a, b, c, 0, 0, 0); }
; template <int MODE, bool MASKED, class MaskF>
; DI void flash_tile(const u16* sK, const u16* sV, const bf16x8 (&qf)[2][2], f32x4 (&O)[2][4], float (&m)[2], float (&l)[2],
;                    float (&ps)[4][4], MaskF ok, bool sel, int lane) {
;     ...
;       mx = fmaxf(mx, __shfl_xor(mx, 16));
;       mx = fmaxf(mx, __shfl_xor(mx, 32));
;       const float mnew = fmaxf(m[qt], mx);
;       const float alpha = __builtin_amdgcn_exp2f(m[qt] - mnew);
;       m[qt] = mnew;
;       float rs = 0.f;
;       if (MASKED) {
; #pragma unroll
;         for (int kt = 0; kt < 4; ++kt)
; #pragma unroll
;           for (int i = 0; i < 4; ++i) {
;             const float pv = (s[kt][i] > -1e29f) ? __builtin_amdgcn_exp2f(s[kt][i] - mnew) : 0.f;
;             pr[kt][i] = pv;
;             rs += pv;
;           }
;       } else {
;         const float me = sel ? mnew : 1e30f;
; #pragma unroll
;         for (int kt = 0; kt < 4; ++kt)
; #pragma unroll
;           for (int i = 0; i < 4; ++i) {
;             const float pv = __builtin_amdgcn_exp2f(s[kt][i] - me);
;             pr[kt][i] = pv;
;             rs += pv;
;           }
;       }
;       l[qt] = l[qt] * alpha + rs;
;       if (MODE == 2) {
; #pragma unroll
;         for (int dt = 0; dt < 4; ++dt) O[qt][dt] *= alpha;
;       }
;     }
;     }
;     if (MODE != 0) {
; #pragma unroll
;       for (int ks2 = 0; ks2 < 2; ++ks2) {
;         pf[qt][ks2].u[0] = pk2(pr[2 * ks2][0], pr[2 * ks2][1]);
;         pf[qt][ks2].u[1] = pk2(pr[2 * ks2][2], pr[2 * ks2][3]);
;         pf[qt][ks2].u[2] = pk2(pr[2 * ks2 + 1][0], pr[2 * ks2 + 1][1]);
;         pf[qt][ks2].u[3] = pk2(pr[2 * ks2 + 1][2], pr[2 * ks2 + 1][3]);
;       }
;     }
;   }
;   if (MODE != 0) {
; #pragma unroll
;     for (int ks2 = 0; ks2 < 2; ++ks2) {
; #pragma unroll
;       for (int dt = 0; dt < 4; ++dt) {
;         union { uint2 h[2]; bf16x8 v; } vf;
;         vf.h[0] = *(const uint2*)(sV + (16 * dt + l15) * 72 + 32 * ks2 + 4 * lg);
;         vf.h[1] = *(const uint2*)(sV + (16 * dt + l15) * 72 + 32 * ks2 + 16 + 4 * lg);
;         O[0][dt] = mfma16(vf.v, pf[0][ks2].v, O[0][dt]);
;         O[1][dt] = mfma16(vf.v, pf[1][ks2].v, O[1][dt]);
	v_pk_mul_f32 v[80:81], v[56:57], v[94:95] op_sel_hi:[1,0]
	v_pk_mul_f32 v[78:79], v[54:55], v[94:95] op_sel_hi:[1,0]
	v_pk_mul_f32 v[56:57], v[52:53], v[94:95] op_sel_hi:[1,0]
	v_pk_mul_f32 v[54:55], v[50:51], v[94:95] op_sel_hi:[1,0]
	v_pk_mul_f32 v[52:53], v[48:49], v[94:95] op_sel_hi:[1,0]
	v_pk_mul_f32 v[50:51], v[46:47], v[94:95] op_sel_hi:[1,0]
	v_mfma_f32_16x16x32_bf16 v[46:49], v[66:69], v[16:19], v[70:73]
	v_cndmask_b32_e64 v66, v148, v91, s[4:5]
	v_cndmask_b32_e64 v77, v77, v148, s[56:57]
	v_add_f32_e32 v115, v112, v115
	v_cndmask_b32_e32 v70, v90, v148, vcc
	v_cndmask_b32_e64 v71, v66, v148, s[36:37]
	v_cndmask_b32_e64 v72, v92, v148, s[38:39]
	v_cndmask_b32_e64 v73, v93, v148, s[40:41]
	s_nop 0
	v_cndmask_b32_e64 v87, v46, v148, s[58:59]
	v_max3_f32 v46, v70, s1, v71
	v_max3_f32 v46, v46, v72, v73
	v_max3_f32 v46, v46, v82, v83
	v_max3_f32 v46, v46, v84, v85
	v_max3_f32 v46, v46, v74, v75
	v_cndmask_b32_e64 v88, v47, v148, s[60:61]
	v_max3_f32 v46, v46, v76, v77
	v_add_f32_e32 v115, v113, v115
	v_cndmask_b32_e64 v89, v48, v148, s[62:63]
	v_cndmask_b32_e64 v90, v49, v148, s[64:65]
	v_max3_f32 v46, v46, v87, v88
	v_add_f32_e32 v115, v102, v115
	v_max3_f32 v66, v46, v89, v90
	v_add_f32_e32 v115, v103, v115
	ds_bpermute_b32 v67, v144, v66
	v_add_f32_e32 v115, v104, v115
	v_add_f32_e32 v115, v105, v115
	v_add_f32_e32 v115, v98, v115
	v_add_f32_e32 v115, v99, v115
	v_cmp_lt_f32_e64 s[66:67], s82, v101
	v_add_f32_e32 v96, v95, v115
	s_waitcnt lgkmcnt(0)
	v_max_f32_e32 v67, v67, v67
	v_cndmask_b32_e64 v86, 0, v97, s[66:67]
	v_add_f32_e32 v168, v86, v96
	v_cvt_pk_bf16_f32 v49, v95, v86
	v_max_f32_e32 v86, v66, v67
	ds_bpermute_b32 v91, v145, v86
	v_cmp_lt_f32_e32 vcc, s82, v70
	v_fmac_f32_e32 v168, v163, v94
	v_pk_mul_f32 v[60:61], v[60:61], v[94:95] op_sel_hi:[1,0]
	v_pk_mul_f32 v[58:59], v[58:59], v[94:95] op_sel_hi:[1,0]
	s_waitcnt lgkmcnt(0)
	v_max3_f32 v169, v166, v86, v91
	v_sub_f32_e32 v91, v70, v169
	v_exp_f32_e32 v91, v91
	v_sub_f32_e32 v92, v71, v169
	v_exp_f32_e32 v92, v92
	v_sub_f32_e32 v70, v72, v169
	v_exp_f32_e32 v70, v70
	v_cndmask_b32_e32 v91, 0, v91, vcc
	v_cmp_lt_f32_e32 vcc, s82, v71
	v_sub_f32_e32 v71, v73, v169
	v_exp_f32_e32 v71, v71
	v_cndmask_b32_e32 v92, 0, v92, vcc
	v_cmp_lt_f32_e32 vcc, s82, v72
	v_cvt_pk_bf16_f32 v48, v98, v99
	v_cvt_pk_bf16_f32 v46, v102, v103
	v_cndmask_b32_e32 v94, 0, v70, vcc
	v_sub_f32_e32 v70, v82, v169
	v_exp_f32_e32 v70, v70
	v_cmp_lt_f32_e32 vcc, s82, v73
	v_lshlrev_b32_e32 v102, 1, v153
	v_add3_u32 v3, s74, v3, v102
	v_cndmask_b32_e32 v95, 0, v71, vcc
	v_sub_f32_e32 v71, v83, v169
	v_cmp_lt_f32_e32 vcc, s82, v82
	v_exp_f32_e32 v71, v71
	v_cvt_pk_bf16_f32 v47, v104, v105
	v_cndmask_b32_e32 v96, 0, v70, vcc
	v_sub_f32_e32 v70, v84, v169
	v_exp_f32_e32 v70, v70
	v_cmp_lt_f32_e32 vcc, s82, v83
	v_add_f32_e32 v93, 0, v91
	v_add_u32_e32 v103, 0x2000, v3
	v_cndmask_b32_e32 v97, 0, v71, vcc
	v_sub_f32_e32 v71, v85, v169
	v_cmp_lt_f32_e32 vcc, s82, v84
	v_exp_f32_e32 v71, v71
	v_sub_f32_e32 v86, v166, v169
	v_cndmask_b32_e32 v98, 0, v70, vcc
	v_sub_f32_e32 v70, v74, v169
	v_exp_f32_e32 v70, v70
	v_cmp_lt_f32_e32 vcc, s82, v85
	v_exp_f32_e32 v86, v86
	v_add3_u32 v0, s74, v0, v102
	v_cndmask_b32_e32 v99, 0, v71, vcc
	v_sub_f32_e32 v71, v75, v169
	v_cmp_lt_f32_e32 vcc, s82, v74
	v_exp_f32_e32 v71, v71
	v_cvt_pk_bf16_f32 v69, v112, v113
	v_cndmask_b32_e32 v100, 0, v70, vcc
	v_sub_f32_e32 v70, v76, v169
	v_exp_f32_e32 v70, v70
	v_cmp_lt_f32_e32 vcc, s82, v75
	v_cvt_pk_bf16_f32 v66, v106, v107
	v_cvt_pk_bf16_f32 v67, v108, v109
	v_cndmask_b32_e32 v101, 0, v71, vcc
	v_sub_f32_e32 v71, v77, v169
	v_cmp_lt_f32_e32 vcc, s82, v76
	v_exp_f32_e32 v71, v71
	v_cvt_pk_bf16_f32 v68, v110, v111
	v_cndmask_b32_e32 v122, 0, v70, vcc
	v_sub_f32_e32 v70, v87, v169
	v_exp_f32_e32 v74, v70
	v_cmp_lt_f32_e32 vcc, s82, v77
	v_cvt_pk_bf16_f32 v75, v94, v95
	v_cvt_pk_bf16_f32 v76, v96, v97
	v_cndmask_b32_e32 v123, 0, v71, vcc
	v_cmp_lt_f32_e32 vcc, s82, v87
	ds_read_b64 v[70:71], v103 offset:1024
	ds_read_b64 v[72:73], v103 offset:1056
	v_cvt_pk_bf16_f32 v77, v98, v99
	v_cndmask_b32_e32 v87, 0, v74, vcc
	v_sub_f32_e32 v74, v88, v169
	v_exp_f32_e32 v104, v74
	v_cvt_pk_bf16_f32 v74, v91, v92
	v_add_u32_e32 v91, 0x2800, v3
	ds_read_b64 v[82:83], v91 offset:1280
	ds_read_b64 v[84:85], v91 offset:1312
	v_pk_mul_f32 v[44:45], v[44:45], v[86:87] op_sel_hi:[1,0]
	v_pk_mul_f32 v[42:43], v[42:43], v[86:87] op_sel_hi:[1,0]
	v_add_u32_e32 v3, 0x3000, v3
	v_pk_mul_f32 v[40:41], v[40:41], v[86:87] op_sel_hi:[1,0]
	v_pk_mul_f32 v[38:39], v[38:39], v[86:87] op_sel_hi:[1,0]
	v_add_u32_e32 v0, 0x2000, v0
	s_waitcnt lgkmcnt(1)
; DI f32x4 mfma16(bf16x8 a, bf16x8 b, f32x4 c) { return __builtin_amdgcn_mfma_f32_16x16x32_bf16(a, b, c, 0, 0, 0); }
; template <int MODE, bool MASKED, class MaskF>
; DI void flash_tile(const u16* sK, const u16* sV, const bf16x8 (&qf)[2][2], f32x4 (&O)[2][4], float (&m)[2], float (&l)[2],
;                    float (&ps)[4][4], MaskF ok, bool sel, int lane) {
;     ...
;       l[qt] = l[qt] * alpha + rs;
;       if (MODE == 2) {
; #pragma unroll
;         for (int dt = 0; dt < 4; ++dt) O[qt][dt] *= alpha;
;       }
;     }
;     }
;     if (MODE != 0) {
; #pragma unroll
;       for (int ks2 = 0; ks2 < 2; ++ks2) {
;         pf[qt][ks2].u[0] = pk2(pr[2 * ks2][0], pr[2 * ks2][1]);
;         pf[qt][ks2].u[1] = pk2(pr[2 * ks2][2], pr[2 * ks2][3]);
;         pf[qt][ks2].u[2] = pk2(pr[2 * ks2 + 1][0], pr[2 * ks2 + 1][1]);
;         pf[qt][ks2].u[3] = pk2(pr[2 * ks2 + 1][2], pr[2 * ks2 + 1][3]);
;       }
;     }
;   }
;   if (MODE != 0) {
; #pragma unroll
;     for (int ks2 = 0; ks2 < 2; ++ks2) {
; #pragma unroll
;       for (int dt = 0; dt < 4; ++dt) {
;         union { uint2 h[2]; bf16x8 v; } vf;
;         vf.h[0] = *(const uint2*)(sV + (16 * dt + l15) * 72 + 32 * ks2 + 4 * lg);
;         vf.h[1] = *(const uint2*)(sV + (16 * dt + l15) * 72 + 32 * ks2 + 16 + 4 * lg);
;         O[0][dt] = mfma16(vf.v, pf[0][ks2].v, O[0][dt]);
;         O[1][dt] = mfma16(vf.v, pf[1][ks2].v, O[1][dt]);
;       }
;     }
	v_mfma_f32_16x16x32_bf16 v[58:61], v[70:73], v[66:69], v[58:61]
	v_cmp_lt_f32_e32 vcc, s82, v88
	v_pk_mul_f32 v[36:37], v[36:37], v[86:87] op_sel_hi:[1,0]
	v_pk_mul_f32 v[34:35], v[34:35], v[86:87] op_sel_hi:[1,0]
	v_mfma_f32_16x16x32_bf16 v[42:45], v[70:73], v[74:77], v[42:45]
	ds_read_b64 v[70:71], v3 offset:1536
	ds_read_b64 v[72:73], v3 offset:1568
	v_cndmask_b32_e32 v88, 0, v104, vcc
	v_sub_f32_e32 v104, v89, v169
	s_waitcnt lgkmcnt(1)
	v_mfma_f32_16x16x32_bf16 v[78:81], v[82:85], v[66:69], v[78:81]
	v_exp_f32_e32 v102, v104
	v_pk_mul_f32 v[32:33], v[32:33], v[86:87] op_sel_hi:[1,0]
	v_pk_mul_f32 v[30:31], v[30:31], v[86:87] op_sel_hi:[1,0]
	v_mfma_f32_16x16x32_bf16 v[38:41], v[82:85], v[74:77], v[38:41]
	ds_read_b64 v[82:83], v0 offset:1024
	ds_read_b64 v[84:85], v0 offset:1056
	v_cmp_lt_f32_e32 vcc, s82, v89
	s_waitcnt lgkmcnt(1)
	v_mfma_f32_16x16x32_bf16 v[54:57], v[70:73], v[66:69], v[54:57]
	v_cndmask_b32_e32 v89, 0, v102, vcc
	v_cmp_lt_f32_e32 vcc, s82, v90
	s_waitcnt lgkmcnt(0)
	v_mfma_f32_16x16x32_bf16 v[50:53], v[82:85], v[66:69], v[50:53]
	ds_read_b64 v[66:67], v103 offset:1088
	ds_read_b64 v[68:69], v103 offset:1120
	v_mfma_f32_16x16x32_bf16 v[34:37], v[70:73], v[74:77], v[34:37]
	v_sub_f32_e32 v70, v90, v169
	v_exp_f32_e32 v70, v70
	v_cvt_pk_bf16_f32 v71, v122, v123
	v_mfma_f32_16x16x32_bf16 v[30:33], v[82:85], v[74:77], v[30:33]
	ds_read_b64 v[74:75], v91 offset:1344
	ds_read_b64 v[76:77], v91 offset:1376
	v_cndmask_b32_e32 v82, 0, v70, vcc
	v_cvt_pk_bf16_f32 v70, v100, v101
	v_cvt_pk_bf16_f32 v72, v87, v88
	v_cvt_pk_bf16_f32 v73, v89, v82
	s_waitcnt lgkmcnt(1)
	v_mfma_f32_16x16x32_bf16 v[102:105], v[66:69], v[46:49], v[58:61]
	v_mfma_f32_16x16x32_bf16 v[106:109], v[66:69], v[70:73], v[42:45]
	s_nop 2
	v_add_f32_e32 v42, v92, v93
	v_add_f32_e32 v58, v94, v42
	ds_read_b64 v[42:43], v3 offset:1600
	ds_read_b64 v[44:45], v3 offset:1632
	v_add_f32_e32 v3, v95, v58
	v_add_f32_e32 v3, v96, v3
	s_waitcnt lgkmcnt(1)
	v_mfma_f32_16x16x32_bf16 v[114:117], v[74:77], v[70:73], v[38:41]
	v_add_f32_e32 v3, v97, v3
	v_add_f32_e32 v3, v98, v3
	v_add_f32_e32 v3, v99, v3
	ds_read_b64 v[38:39], v0 offset:1088
	ds_read_b64 v[40:41], v0 offset:1120
	v_add_f32_e32 v0, v100, v3
	v_add_f32_e32 v0, v101, v0
	v_add_f32_e32 v0, v122, v0
	v_add_f32_e32 v0, v123, v0
	v_add_f32_e32 v0, v87, v0
	v_mfma_f32_16x16x32_bf16 v[110:113], v[74:77], v[46:49], v[78:81]
	v_add_f32_e32 v0, v88, v0
	v_add_f32_e32 v0, v89, v0
	v_add_f32_e32 v170, v82, v0
	s_waitcnt lgkmcnt(1)
	v_mfma_f32_16x16x32_bf16 v[118:121], v[42:45], v[46:49], v[54:57]
	v_fmac_f32_e32 v170, v162, v86
	v_mfma_f32_16x16x32_bf16 v[126:129], v[42:45], v[70:73], v[34:37]
	s_waitcnt lgkmcnt(0)
	v_mfma_f32_16x16x32_bf16 v[98:101], v[38:41], v[46:49], v[50:53]
	v_mfma_f32_16x16x32_bf16 v[122:125], v[38:41], v[70:73], v[30:33]

; DI f32x4 mfma16(bf16x8 a, bf16x8 b, f32x4 c) { return __builtin_amdgcn_mfma_f32_16x16x32_bf16(a, b, c, 0, 0, 0); }
; template <bool MASKED, class MaskF>
; DI void flash_pv3(const u16* sV, const f32x4 (&s)[2][4], f32x4 (&O)[2][4], float (&l)[2], MaskF ok, int lane) {
;     ...
; #pragma unroll
;   for (int ks2 = 0; ks2 < 2; ++ks2) {
; #pragma unroll
;     for (int dt = 0; dt < 4; ++dt) {
;       union { uint2 h[2]; bf16x8 v; } vf;
;       vf.h[0] = *(const uint2*)(sV + (16 * dt + l15) * 72 + 32 * ks2 + 4 * lg);
;       vf.h[1] = *(const uint2*)(sV + (16 * dt + l15) * 72 + 32 * ks2 + 16 + 4 * lg);
;       O[0][dt] = mfma16(vf.v, pf[0][ks2].v, O[0][dt]);
;       O[1][dt] = mfma16(vf.v, pf[1][ks2].v, O[1][dt]);
;     }
;   }
.Lmy_sel_pv:
	s_add_i32 s40, s45, 32
	v_add3_u32 v198, s40, v160, v159
	v_add3_u32 v206, s40, v3, v159
	v_add_u32_e32 v214, 0x2000, v198
	v_add_u32_e32 v215, 0x2800, v198
	v_add_u32_e32 v216, 0x3000, v198
	v_add_u32_e32 v217, 0x2000, v206
	ds_read_b64 v[114:115], v214 offset:1024
	ds_read_b64 v[116:117], v214 offset:1056
	ds_read_b64 v[122:123], v215 offset:1280
	ds_read_b64 v[124:125], v215 offset:1312
	ds_read_b64 v[198:199], v216 offset:1536
	ds_read_b64 v[200:201], v216 offset:1568
	ds_read_b64 v[206:207], v217 offset:1024
	ds_read_b64 v[208:209], v217 offset:1056
	ds_read_b64 v[118:119], v214 offset:1088
	ds_read_b64 v[120:121], v214 offset:1120
	ds_read_b64 v[126:127], v215 offset:1344
	ds_read_b64 v[128:129], v215 offset:1376
	ds_read_b64 v[202:203], v216 offset:1600
	ds_read_b64 v[204:205], v216 offset:1632
	ds_read_b64 v[210:211], v217 offset:1088
	ds_read_b64 v[212:213], v217 offset:1120
	v_cvt_pk_bf16_f32 v106, v197, v195
	v_cvt_pk_bf16_f32 v107, v194, v193
	v_cvt_pk_bf16_f32 v108, v192, v191
	v_cvt_pk_bf16_f32 v109, v190, v189
	v_cvt_pk_bf16_f32 v110, v179, v180
	v_cvt_pk_bf16_f32 v111, v165, v166
	v_cvt_pk_bf16_f32 v112, v167, v168
	v_cvt_pk_bf16_f32 v113, v169, v170
	v_cvt_pk_bf16_f32 v98, v188, v187
	v_cvt_pk_bf16_f32 v99, v186, v185
	v_cvt_pk_bf16_f32 v100, v184, v183
	v_cvt_pk_bf16_f32 v101, v182, v181
	v_cvt_pk_bf16_f32 v102, v171, v172
	v_cvt_pk_bf16_f32 v103, v173, v174
	v_cvt_pk_bf16_f32 v104, v175, v176
	v_cvt_pk_bf16_f32 v105, v177, v178
	s_waitcnt lgkmcnt(14)
	v_mfma_f32_16x16x32_bf16 v[58:61], v[114:117], v[106:109], v[58:61]
	v_add_f32_e32 v0, 0, v197
	v_add_f32_e32 v2, 0, v179
	v_mfma_f32_16x16x32_bf16 v[42:45], v[114:117], v[110:113], v[42:45]
	v_add_f32_e32 v0, v195, v0
	v_add_f32_e32 v2, v180, v2
	s_waitcnt lgkmcnt(12)
	v_mfma_f32_16x16x32_bf16 v[54:57], v[122:125], v[106:109], v[54:57]
	v_add_f32_e32 v0, v194, v0
	v_add_f32_e32 v2, v165, v2
	v_mfma_f32_16x16x32_bf16 v[38:41], v[122:125], v[110:113], v[38:41]
	v_add_f32_e32 v0, v193, v0
	v_add_f32_e32 v2, v166, v2
	s_waitcnt lgkmcnt(10)
	v_mfma_f32_16x16x32_bf16 v[50:53], v[198:201], v[106:109], v[50:53]
	v_add_f32_e32 v0, v192, v0
	v_add_f32_e32 v2, v167, v2
	v_mfma_f32_16x16x32_bf16 v[34:37], v[198:201], v[110:113], v[34:37]
	v_add_f32_e32 v0, v191, v0
	v_add_f32_e32 v2, v168, v2
	s_waitcnt lgkmcnt(8)
	v_mfma_f32_16x16x32_bf16 v[46:49], v[206:209], v[106:109], v[46:49]
	v_add_f32_e32 v0, v190, v0
	v_add_f32_e32 v2, v169, v2
	v_mfma_f32_16x16x32_bf16 v[30:33], v[206:209], v[110:113], v[30:33]
	v_add_f32_e32 v0, v189, v0
	v_add_f32_e32 v2, v170, v2
	s_waitcnt lgkmcnt(6)
	v_mfma_f32_16x16x32_bf16 v[58:61], v[118:121], v[98:101], v[58:61]
	v_add_f32_e32 v0, v188, v0
	v_add_f32_e32 v2, v171, v2
	v_mfma_f32_16x16x32_bf16 v[42:45], v[118:121], v[102:105], v[42:45]
	v_add_f32_e32 v0, v187, v0
	v_add_f32_e32 v2, v172, v2
	s_waitcnt lgkmcnt(4)
	v_mfma_f32_16x16x32_bf16 v[54:57], v[126:129], v[98:101], v[54:57]
	v_add_f32_e32 v0, v186, v0
	v_add_f32_e32 v2, v173, v2
	v_mfma_f32_16x16x32_bf16 v[38:41], v[126:129], v[102:105], v[38:41]
	v_add_f32_e32 v0, v185, v0
	v_add_f32_e32 v2, v174, v2
	s_waitcnt lgkmcnt(2)
	v_mfma_f32_16x16x32_bf16 v[50:53], v[202:205], v[98:101], v[50:53]
	v_add_f32_e32 v0, v184, v0
	v_add_f32_e32 v2, v175, v2
	v_mfma_f32_16x16x32_bf16 v[34:37], v[202:205], v[102:105], v[34:37]
	v_add_f32_e32 v0, v183, v0
	v_add_f32_e32 v2, v176, v2
	s_waitcnt lgkmcnt(0)
	v_mfma_f32_16x16x32_bf16 v[46:49], v[210:213], v[98:101], v[46:49]
	v_add_f32_e32 v0, v182, v0
	v_add_f32_e32 v2, v177, v2
	v_mfma_f32_16x16x32_bf16 v[30:33], v[210:213], v[102:105], v[30:33]
	v_add_f32_e32 v0, v181, v0
	v_add_f32_e32 v2, v178, v2
	v_add_f32_e32 v163, v163, v0
	v_add_f32_e32 v162, v162, v2

; template <int MODE, bool MASKED, class MaskF>
; DI void flash_tile(const u16* sK, const u16* sV, const bf16x8 (&qf)[2][2], f32x4 (&O)[2][4], float (&m)[2], float (&l)[2],
;                    float (&ps)[4][4], MaskF ok, bool sel, int lane) {
;     ...
;   for (int qt = 0; qt < 2; ++qt) {
;     f32x4 s[4];
;     const float sinit = (MODE == 3) ? ((MASKED || sel) ? m[qt] : -1e30f) : 0.f;
; #pragma unroll
;     for (int kt = 0; kt < 4; ++kt) {
;       s[kt] = f32x4{sinit, sinit, sinit, sinit};
; #pragma unroll
;       for (int ks = 0; ks < 2; ++ks) s[kt] = mfma16(kf[kt][ks], qf[qt][ks], s[kt]);
;     }
;     float pr[4][4];
;     if (MODE == 3) {
;       float rs = 0.f;
; #pragma unroll
;       for (int kt = 0; kt < 4; ++kt)
; #pragma unroll
;         for (int i = 0; i < 4; ++i) {
;           float pv = __builtin_amdgcn_exp2f(s[kt][i]);
;           if (MASKED) pv = ok(kt, i) ? pv : 0.f;
;           pr[kt][i] = pv;
;           rs += pv;
;         }
;       l[qt] += rs;
;     } else {
;     float mx = -1e30f;
; #pragma unroll
;     for (int kt = 0; kt < 4; ++kt)
; #pragma unroll
;       for (int i = 0; i < 4; ++i) {
;         if (MASKED) s[kt][i] = ok(kt, i) ? s[kt][i] : -1e30f;
;         mx = fmaxf(mx, s[kt][i]);
;       }
;     if (!MASKED) mx = sel ? mx : -1e30f;
;     if (MODE == 1) {
;       const float mm = m[qt], il = l[qt];
; #pragma unroll
;       for (int kt = 0; kt < 4; ++kt)
; #pragma unroll
;         for (int i = 0; i < 4; ++i) {
;           const float pv = (s[kt][i] > -1e29f) ? __builtin_amdgcn_exp2f(s[kt][i] - mm) * il : 0.f;
;           pr[kt][i] = pv;
;           ps[kt][i] += pv;
;         }
;     } else {
; DI void nsa_item(int wv0, PP p, int item, unsigned char* smem) {
;     ...
;     for (int j = j0; j <= i; ++j) {
;       const u16* cK = sK + cur * 9216;
;       const u16* cV = sV + cur * 9216;
;       if (j == i || j == i - 8) {
;         auto ok = [&](int kt, int ii) {
;           const int kp = j * 64 + 16 * kt + 4 * lg + ii;
;           return kp <= tq && kp > tq - 512;
;         };
;         if (usefix) flash_tile<3, true>(cK, cV, qf, O, m, l, ps, ok, true, lane);
;         else flash_tile<2, true>(cK, cV, qf, O, m, l, ps, ok, true, lane);
;       } else {
;         if (usefix) flash_tile<3, false>(cK, cV, qf, O, m, l, ps, nomask, true, lane);
;         else flash_tile<2, false>(cK, cV, qf, O, m, l, ps, nomask, true, lane);
.LBB0_904:
	s_mul_i32 s6, s85, 0x4800
	v_add_u32_e32 v25, s6, v155
	v_lshl_add_u32 v26, v0, 1, v25
	ds_read_b128 v[96:99], v26
	ds_read_b128 v[92:95], v26 offset:64
	ds_read_b128 v[88:91], v26 offset:2304
	ds_read_b128 v[84:87], v26 offset:2368
	ds_read_b128 v[80:83], v26 offset:4608
	ds_read_b128 v[76:79], v26 offset:4672
	s_add_i32 s4, s88, s84
	s_add_i32 s74, s6, 32
	v_lshl_add_u32 v25, v2, 1, v25
	s_cmpk_eq_i32 s4, 0x81
	ds_read_b128 v[72:75], v25
	ds_read_b128 v[68:71], v25 offset:64
	s_cselect_b64 s[2:3], -1, 0
	s_cmpk_eq_i32 s4, 0x79
	s_cselect_b64 s[4:5], -1, 0
	s_or_b64 s[2:3], s[2:3], s[4:5]
	v_mov_b32_e32 v60, v104
	v_mov_b32_e32 v61, v105
	v_mov_b32_e32 v62, v106
	v_mov_b32_e32 v63, v107
	v_mov_b32_e32 v52, v112
	v_mov_b32_e32 v53, v113
	v_mov_b32_e32 v54, v114
	v_mov_b32_e32 v55, v115
	v_mov_b32_e32 v44, v120
	v_mov_b32_e32 v45, v121
	v_mov_b32_e32 v46, v122
	v_mov_b32_e32 v47, v123
	v_mov_b32_e32 v36, v128
	v_mov_b32_e32 v37, v129
	v_mov_b32_e32 v38, v130
	v_mov_b32_e32 v39, v131
	v_mov_b32_e32 v64, v100
	v_mov_b32_e32 v65, v101
	v_mov_b32_e32 v66, v102
	v_mov_b32_e32 v67, v103
	v_mov_b32_e32 v56, v108
	v_mov_b32_e32 v57, v109
	v_mov_b32_e32 v58, v110
	v_mov_b32_e32 v59, v111
	v_mov_b32_e32 v48, v116
	v_mov_b32_e32 v49, v117
	v_mov_b32_e32 v50, v118
	v_mov_b32_e32 v51, v119
	v_mov_b32_e32 v40, v124
	v_mov_b32_e32 v41, v125
	v_mov_b32_e32 v42, v126
	v_mov_b32_e32 v43, v127
	s_andn2_b64 vcc, exec, s[2:3]
	s_mov_b64 s[2:3], -1
	s_cbranch_vccz .LBB0_909
	s_and_b64 vcc, exec, s[90:91]
	s_cbranch_vccz .LBB0_919
	s_waitcnt lgkmcnt(7)
	v_mfma_f32_16x16x32_bf16 v[100:103], v[96:99], v[4:7], 0
	s_waitcnt lgkmcnt(5)
	v_mfma_f32_16x16x32_bf16 v[104:107], v[88:91], v[4:7], 0
	v_mfma_f32_16x16x32_bf16 v[100:103], v[92:95], v[8:11], v[100:103]
	s_waitcnt lgkmcnt(3)
	v_mfma_f32_16x16x32_bf16 v[108:111], v[80:83], v[4:7], 0
	v_mfma_f32_16x16x32_bf16 v[104:107], v[84:87], v[8:11], v[104:107]
	s_nop 4
	v_max3_f32 v25, v100, s1, v101
	v_max3_f32 v25, v25, v102, v103
	s_waitcnt lgkmcnt(1)
	v_mfma_f32_16x16x32_bf16 v[112:115], v[72:75], v[4:7], 0
	v_mfma_f32_16x16x32_bf16 v[108:111], v[76:79], v[8:11], v[108:111]
	v_max3_f32 v25, v25, v104, v105
	v_max3_f32 v25, v25, v106, v107
	s_waitcnt lgkmcnt(0)
	v_mfma_f32_16x16x32_bf16 v[112:115], v[68:71], v[8:11], v[112:115]
	v_mfma_f32_16x16x32_bf16 v[132:135], v[80:83], v[12:15], 0
	s_nop 2
	v_max3_f32 v25, v25, v108, v109
	v_max3_f32 v25, v25, v110, v111
	s_nop 1
	v_max3_f32 v25, v25, v112, v113
	v_max3_f32 v25, v25, v114, v115
	ds_bpermute_b32 v26, v144, v25
	v_mfma_f32_16x16x32_bf16 v[160:163], v[72:75], v[12:15], 0
	s_waitcnt lgkmcnt(0)
	v_max_f32_e32 v26, v26, v26
	v_max_f32_e32 v25, v25, v26
	ds_bpermute_b32 v26, v145, v25
	v_mfma_f32_16x16x32_bf16 v[132:135], v[76:79], v[16:19], v[132:135]
	s_waitcnt lgkmcnt(0)
	v_max3_f32 v25, v28, v25, v26
	v_sub_f32_e32 v27, v100, v25
	v_exp_f32_e32 v27, v27
	v_sub_f32_e32 v30, v101, v25
	v_exp_f32_e32 v30, v30
	v_sub_f32_e32 v31, v102, v25
	v_exp_f32_e32 v31, v31
	v_sub_f32_e32 v100, v103, v25
	v_exp_f32_e32 v120, v100
	v_sub_f32_e32 v100, v104, v25
	v_add_f32_e32 v29, 0, v27
	v_exp_f32_e32 v121, v100
	v_sub_f32_e32 v100, v105, v25
	v_add_f32_e32 v29, v30, v29
	v_exp_f32_e32 v122, v100
	v_sub_f32_e32 v100, v106, v25
	v_add_f32_e32 v29, v31, v29
	v_exp_f32_e32 v123, v100
	v_sub_f32_e32 v100, v107, v25
	v_add_f32_e32 v29, v120, v29
	v_exp_f32_e32 v107, v100
	v_sub_f32_e32 v100, v108, v25
	v_add_f32_e32 v29, v121, v29
	v_exp_f32_e32 v124, v100
	v_sub_f32_e32 v100, v109, v25
	v_add_f32_e32 v29, v122, v29
	v_exp_f32_e32 v125, v100
	v_sub_f32_e32 v100, v110, v25
	v_add_f32_e32 v29, v123, v29
	v_exp_f32_e32 v126, v100
	v_sub_f32_e32 v100, v111, v25
	v_add_f32_e32 v29, v107, v29
	v_exp_f32_e32 v127, v100
	v_sub_f32_e32 v100, v112, v25
	v_add_f32_e32 v29, v124, v29
	v_exp_f32_e32 v128, v100
	v_sub_f32_e32 v100, v113, v25
	v_add_f32_e32 v29, v125, v29
	v_exp_f32_e32 v129, v100
	v_sub_f32_e32 v100, v114, v25
	v_add_f32_e32 v29, v126, v29
	v_exp_f32_e32 v130, v100
	v_sub_f32_e32 v100, v115, v25
	v_add_f32_e32 v29, v127, v29
	v_exp_f32_e32 v131, v100
	v_add_f32_e32 v29, v128, v29
	v_add_f32_e32 v29, v129, v29
	v_cvt_pk_bf16_f32 v105, v31, v120
	v_cvt_pk_bf16_f32 v106, v121, v122
	v_cvt_pk_bf16_f32 v107, v123, v107
	v_mfma_f32_16x16x32_bf16 v[120:123], v[96:99], v[12:15], 0
	v_add_f32_e32 v29, v130, v29
	v_add_f32_e32 v29, v131, v29
	v_cvt_pk_bf16_f32 v124, v124, v125
	v_cvt_pk_bf16_f32 v125, v126, v127
	v_cvt_pk_bf16_f32 v126, v128, v129
	v_cvt_pk_bf16_f32 v127, v130, v131
	v_mfma_f32_16x16x32_bf16 v[128:131], v[88:91], v[12:15], 0
	v_sub_f32_e32 v26, v28, v25
	v_exp_f32_e32 v26, v26
	v_cvt_pk_bf16_f32 v104, v27, v30
	v_mfma_f32_16x16x32_bf16 v[120:123], v[92:95], v[16:19], v[120:123]
	v_fmac_f32_e32 v29, v158, v26
	v_pk_mul_f32 v[118:119], v[62:63], v[26:27] op_sel_hi:[1,0]
	v_mfma_f32_16x16x32_bf16 v[128:131], v[84:87], v[16:19], v[128:131]
	v_mul_f32_e64 v116, v60, v26
	v_mul_f32_e64 v117, v61, v26
	v_pk_mul_f32 v[114:115], v[54:55], v[26:27] op_sel_hi:[1,0]
	v_pk_mul_f32 v[112:113], v[52:53], v[26:27] op_sel_hi:[1,0]
	v_pk_mul_f32 v[110:111], v[46:47], v[26:27] op_sel_hi:[1,0]
	v_pk_mul_f32 v[108:109], v[44:45], v[26:27] op_sel_hi:[1,0]
	v_pk_mul_f32 v[102:103], v[38:39], v[26:27] op_sel_hi:[1,0]
	v_pk_mul_f32 v[100:101], v[36:37], v[26:27] op_sel_hi:[1,0]
	v_max3_f32 v26, v120, s1, v121
	v_max3_f32 v26, v26, v122, v123
	v_mfma_f32_16x16x32_bf16 v[160:163], v[68:71], v[16:19], v[160:163]
	v_max3_f32 v26, v26, v128, v129
	v_max3_f32 v26, v26, v130, v131
	v_max3_f32 v26, v26, v132, v133
	v_max3_f32 v26, v26, v134, v135
	s_nop 3
	v_max3_f32 v26, v26, v160, v161
	v_max3_f32 v26, v26, v162, v163
	ds_bpermute_b32 v27, v144, v26
	s_waitcnt lgkmcnt(0)
; DI f32x4 mfma16(bf16x8 a, bf16x8 b, f32x4 c) { return __builtin_amdgcn_mfma_f32_16x16x32_bf16(a, b, c, 0, 0, 0); }
; template <int MODE, bool MASKED, class MaskF>
; DI void flash_tile(const u16* sK, const u16* sV, const bf16x8 (&qf)[2][2], f32x4 (&O)[2][4], float (&m)[2], float (&l)[2],
;                    float (&ps)[4][4], MaskF ok, bool sel, int lane) {
;     ...
;       mx = fmaxf(mx, __shfl_xor(mx, 16));
;       mx = fmaxf(mx, __shfl_xor(mx, 32));
;       const float mnew = fmaxf(m[qt], mx);
;       const float alpha = __builtin_amdgcn_exp2f(m[qt] - mnew);
;       m[qt] = mnew;
;       float rs = 0.f;
;       if (MASKED) {
; #pragma unroll
;         for (int kt = 0; kt < 4; ++kt)
; #pragma unroll
;           for (int i = 0; i < 4; ++i) {
;             const float pv = (s[kt][i] > -1e29f) ? __builtin_amdgcn_exp2f(s[kt][i] - mnew) : 0.f;
;             pr[kt][i] = pv;
;             rs += pv;
;           }
;       } else {
;         const float me = sel ? mnew : 1e30f;
; #pragma unroll
;         for (int kt = 0; kt < 4; ++kt)
; #pragma unroll
;           for (int i = 0; i < 4; ++i) {
;             const float pv = __builtin_amdgcn_exp2f(s[kt][i] - me);
;             pr[kt][i] = pv;
;             rs += pv;
;           }
;       }
;       l[qt] = l[qt] * alpha + rs;
;       if (MODE == 2) {
; #pragma unroll
;         for (int dt = 0; dt < 4; ++dt) O[qt][dt] *= alpha;
;       }
;     }
;     }
;     if (MODE != 0) {
; #pragma unroll
;       for (int ks2 = 0; ks2 < 2; ++ks2) {
;         pf[qt][ks2].u[0] = pk2(pr[2 * ks2][0], pr[2 * ks2][1]);
;         pf[qt][ks2].u[1] = pk2(pr[2 * ks2][2], pr[2 * ks2][3]);
;         pf[qt][ks2].u[2] = pk2(pr[2 * ks2 + 1][0], pr[2 * ks2 + 1][1]);
;         pf[qt][ks2].u[3] = pk2(pr[2 * ks2 + 1][2], pr[2 * ks2 + 1][3]);
;       }
;     }
;   }
;   if (MODE != 0) {
; #pragma unroll
;     for (int ks2 = 0; ks2 < 2; ++ks2) {
; #pragma unroll
;       for (int dt = 0; dt < 4; ++dt) {
;         union { uint2 h[2]; bf16x8 v; } vf;
;         vf.h[0] = *(const uint2*)(sV + (16 * dt + l15) * 72 + 32 * ks2 + 4 * lg);
;         vf.h[1] = *(const uint2*)(sV + (16 * dt + l15) * 72 + 32 * ks2 + 16 + 4 * lg);
;         O[0][dt] = mfma16(vf.v, pf[0][ks2].v, O[0][dt]);
;         O[1][dt] = mfma16(vf.v, pf[1][ks2].v, O[1][dt]);
;       }
;     }
	v_max_f32_e32 v27, v27, v27
	v_max_f32_e32 v26, v26, v27
	ds_bpermute_b32 v27, v145, v26
	s_waitcnt lgkmcnt(0)
	v_max3_f32 v27, v24, v26, v27
	v_sub_f32_e32 v26, v120, v27
	v_exp_f32_e32 v31, v26
	v_sub_f32_e32 v120, v121, v27
	v_exp_f32_e32 v159, v120
	v_sub_f32_e32 v120, v122, v27
	v_exp_f32_e32 v169, v120
	v_sub_f32_e32 v120, v123, v27
	v_exp_f32_e32 v170, v120
	v_sub_f32_e32 v120, v128, v27
	v_add_f32_e32 v26, 0, v31
	v_exp_f32_e32 v171, v120
	v_sub_f32_e32 v120, v129, v27
	v_add_f32_e32 v26, v159, v26
	v_exp_f32_e32 v172, v120
	v_sub_f32_e32 v120, v130, v27
	v_add_f32_e32 v26, v169, v26
	v_exp_f32_e32 v173, v120
	v_sub_f32_e32 v120, v131, v27
	v_add_f32_e32 v26, v170, v26
	v_exp_f32_e32 v174, v120
	v_sub_f32_e32 v120, v132, v27
	v_add_f32_e32 v26, v171, v26
	v_exp_f32_e32 v132, v120
	v_sub_f32_e32 v120, v133, v27
	v_add_f32_e32 v26, v172, v26
	v_exp_f32_e32 v133, v120
	v_sub_f32_e32 v120, v134, v27
	v_add_f32_e32 v26, v173, v26
	v_exp_f32_e32 v134, v120
	v_sub_f32_e32 v120, v135, v27
	v_add_f32_e32 v26, v174, v26
	v_exp_f32_e32 v135, v120
	v_sub_f32_e32 v120, v160, v27
	v_add_f32_e32 v26, v132, v26
	v_exp_f32_e32 v175, v120
	v_sub_f32_e32 v120, v161, v27
	v_add_f32_e32 v26, v133, v26
	v_exp_f32_e32 v176, v120
	v_sub_f32_e32 v120, v162, v27
	v_add_f32_e32 v26, v134, v26
	v_exp_f32_e32 v177, v120
	v_sub_f32_e32 v120, v163, v27
	v_sub_f32_e32 v30, v24, v27
	v_add_f32_e32 v26, v135, v26
	v_exp_f32_e32 v178, v120
	v_add_f32_e32 v26, v175, v26
	v_exp_f32_e32 v30, v30
	v_add_f32_e32 v26, v176, v26
	v_add_f32_e32 v26, v177, v26
	v_add_f32_e32 v26, v178, v26
	v_fmac_f32_e32 v26, v157, v30
	v_pk_mul_f32 v[122:123], v[66:67], v[30:31] op_sel_hi:[1,0]
	v_pk_mul_f32 v[120:121], v[64:65], v[30:31] op_sel_hi:[1,0]
	v_pk_mul_f32 v[130:131], v[58:59], v[30:31] op_sel_hi:[1,0]
	v_pk_mul_f32 v[128:129], v[56:57], v[30:31] op_sel_hi:[1,0]
	v_pk_mul_f32 v[162:163], v[50:51], v[30:31] op_sel_hi:[1,0]
	v_pk_mul_f32 v[160:161], v[48:49], v[30:31] op_sel_hi:[1,0]
	v_pk_mul_f32 v[166:167], v[42:43], v[30:31] op_sel_hi:[1,0]
	v_pk_mul_f32 v[164:165], v[40:41], v[30:31] op_sel_hi:[1,0]
	v_cvt_pk_bf16_f32 v168, v31, v159
	v_lshlrev_b32_e32 v30, 1, v0
	v_lshlrev_b32_e32 v31, 1, v153
	v_add3_u32 v30, s74, v30, v31
	v_add_u32_e32 v159, 0x2000, v30
	v_cvt_pk_bf16_f32 v169, v169, v170
	v_cvt_pk_bf16_f32 v170, v171, v172
	v_cvt_pk_bf16_f32 v171, v173, v174
	v_cvt_pk_bf16_f32 v132, v132, v133
	v_cvt_pk_bf16_f32 v133, v134, v135
	v_cvt_pk_bf16_f32 v134, v175, v176
	ds_read_b64 v[172:173], v159 offset:1024
	ds_read_b64 v[174:175], v159 offset:1056
	v_add_u32_e32 v180, 0x2800, v30
	s_waitcnt lgkmcnt(0)
	v_mfma_f32_16x16x32_bf16 v[116:119], v[172:175], v[104:107], v[116:119]
	v_add_u32_e32 v30, 0x3000, v30
	v_cvt_pk_bf16_f32 v135, v177, v178
	v_mfma_f32_16x16x32_bf16 v[120:123], v[172:175], v[168:171], v[120:123]
	ds_read_b64 v[172:173], v180 offset:1280
	ds_read_b64 v[174:175], v180 offset:1312
	s_waitcnt lgkmcnt(0)
	v_mfma_f32_16x16x32_bf16 v[112:115], v[172:175], v[104:107], v[112:115]
	v_mfma_f32_16x16x32_bf16 v[128:131], v[172:175], v[168:171], v[128:131]
	ds_read_b64 v[172:173], v30 offset:1536
	ds_read_b64 v[174:175], v30 offset:1568
	s_waitcnt lgkmcnt(0)
	v_mfma_f32_16x16x32_bf16 v[176:179], v[172:175], v[104:107], v[108:111]
	s_nop 2
	v_lshlrev_b32_e32 v108, 1, v2
	v_add3_u32 v31, s74, v108, v31
	v_add_u32_e32 v31, 0x2000, v31
	ds_read_b64 v[108:109], v31 offset:1024
	ds_read_b64 v[110:111], v31 offset:1056
	v_mfma_f32_16x16x32_bf16 v[160:163], v[172:175], v[168:171], v[160:163]
	s_waitcnt lgkmcnt(0)
	v_mfma_f32_16x16x32_bf16 v[172:175], v[108:111], v[104:107], v[100:103]
	s_nop 2
	ds_read_b64 v[100:101], v159 offset:1088
	ds_read_b64 v[102:103], v159 offset:1120
	s_waitcnt lgkmcnt(0)
	v_mfma_f32_16x16x32_bf16 v[104:107], v[100:103], v[124:127], v[116:119]
	s_nop 2
	ds_read_b64 v[116:117], v30 offset:1600
	ds_read_b64 v[118:119], v30 offset:1632
	v_mfma_f32_16x16x32_bf16 v[164:167], v[108:111], v[168:171], v[164:167]
	ds_read_b64 v[108:109], v180 offset:1344
	ds_read_b64 v[110:111], v180 offset:1376
	v_mfma_f32_16x16x32_bf16 v[100:103], v[100:103], v[132:135], v[120:123]
	s_waitcnt lgkmcnt(1)
	v_mfma_f32_16x16x32_bf16 v[120:123], v[116:119], v[124:127], v[176:179]
	v_mfma_f32_16x16x32_bf16 v[116:119], v[116:119], v[132:135], v[160:163]
	s_nop 2
	ds_read_b64 v[160:161], v31 offset:1088
	ds_read_b64 v[162:163], v31 offset:1120
	s_waitcnt lgkmcnt(1)
	v_mfma_f32_16x16x32_bf16 v[112:115], v[108:111], v[124:127], v[112:115]
	v_mfma_f32_16x16x32_bf16 v[108:111], v[108:111], v[132:135], v[128:131]
	s_waitcnt lgkmcnt(0)
	v_mfma_f32_16x16x32_bf16 v[128:131], v[160:163], v[124:127], v[172:175]
	v_mfma_f32_16x16x32_bf16 v[124:127], v[160:163], v[132:135], v[164:167]
	s_cbranch_execnz .LBB0_908
; DI f32x4 mfma16(bf16x8 a, bf16x8 b, f32x4 c) { return __builtin_amdgcn_mfma_f32_16x16x32_bf16(a, b, c, 0, 0, 0); }
; template <int MODE, bool MASKED, class MaskF>
; DI void flash_tile(const u16* sK, const u16* sV, const bf16x8 (&qf)[2][2], f32x4 (&O)[2][4], float (&m)[2], float (&l)[2],
;                    float (&ps)[4][4], MaskF ok, bool sel, int lane) {
;     ...
;   for (int qt = 0; qt < 2; ++qt) {
;     f32x4 s[4];
;     const float sinit = (MODE == 3) ? ((MASKED || sel) ? m[qt] : -1e30f) : 0.f;
; #pragma unroll
;     for (int kt = 0; kt < 4; ++kt) {
;       s[kt] = f32x4{sinit, sinit, sinit, sinit};
; #pragma unroll
;       for (int ks = 0; ks < 2; ++ks) s[kt] = mfma16(kf[kt][ks], qf[qt][ks], s[kt]);
;     }
;     float pr[4][4];
;     if (MODE == 3) {
;       float rs = 0.f;
; #pragma unroll
;       for (int kt = 0; kt < 4; ++kt)
; #pragma unroll
;         for (int i = 0; i < 4; ++i) {
;           float pv = __builtin_amdgcn_exp2f(s[kt][i]);
;           if (MASKED) pv = ok(kt, i) ? pv : 0.f;
;           pr[kt][i] = pv;
;           rs += pv;
;         }
;       l[qt] += rs;
;     ...
;   if (MODE != 0) {
; #pragma unroll
;     for (int ks2 = 0; ks2 < 2; ++ks2) {
; #pragma unroll
;       for (int dt = 0; dt < 4; ++dt) {
;         union { uint2 h[2]; bf16x8 v; } vf;
;         vf.h[0] = *(const uint2*)(sV + (16 * dt + l15) * 72 + 32 * ks2 + 4 * lg);
;         vf.h[1] = *(const uint2*)(sV + (16 * dt + l15) * 72 + 32 * ks2 + 16 + 4 * lg);
;         O[0][dt] = mfma16(vf.v, pf[0][ks2].v, O[0][dt]);
;         O[1][dt] = mfma16(vf.v, pf[1][ks2].v, O[1][dt]);
;       }
;     }
.LBB0_907:
	v_mov_b32_e32 v29, v28
	v_mov_b32_e32 v30, v28
	v_mov_b32_e32 v31, v28
	v_lshlrev_b32_e32 v159, 1, v2
	s_waitcnt lgkmcnt(7)
	v_mfma_f32_16x16x32_bf16 v[100:103], v[96:99], v[4:7], v[28:31]
	s_waitcnt lgkmcnt(6)
	v_mfma_f32_16x16x32_bf16 v[100:103], v[92:95], v[8:11], v[100:103]
	s_waitcnt lgkmcnt(5)
	v_mfma_f32_16x16x32_bf16 v[104:107], v[88:91], v[4:7], v[28:31]
	s_waitcnt lgkmcnt(4)
	v_mfma_f32_16x16x32_bf16 v[104:107], v[84:87], v[8:11], v[104:107]
	s_nop 3
	v_exp_f32_e32 v25, v100
	v_exp_f32_e32 v27, v101
	v_add_f32_e32 v26, 0, v25
	s_waitcnt lgkmcnt(3)
	v_mfma_f32_16x16x32_bf16 v[108:111], v[80:83], v[4:7], v[28:31]
	v_add_f32_e32 v26, v27, v26
	v_cvt_pk_bf16_f32 v100, v25, v27
	v_mov_b32_e32 v25, v24
	s_waitcnt lgkmcnt(1)
	v_mfma_f32_16x16x32_bf16 v[112:115], v[72:75], v[4:7], v[28:31]
	v_mov_b32_e32 v27, v24
	s_nop 1
	v_exp_f32_e32 v30, v102
	v_exp_f32_e32 v31, v103
	v_mfma_f32_16x16x32_bf16 v[108:111], v[76:79], v[8:11], v[108:111]
	v_exp_f32_e32 v102, v104
	v_exp_f32_e32 v103, v105
	v_add_f32_e32 v26, v30, v26
	v_exp_f32_e32 v104, v106
	v_add_f32_e32 v26, v31, v26
	v_exp_f32_e32 v105, v107
	s_waitcnt lgkmcnt(0)
	v_mfma_f32_16x16x32_bf16 v[112:115], v[68:71], v[8:11], v[112:115]
	v_add_f32_e32 v26, v102, v26
	v_exp_f32_e32 v106, v108
	v_add_f32_e32 v26, v103, v26
	v_exp_f32_e32 v107, v109
	v_add_f32_e32 v26, v104, v26
	v_exp_f32_e32 v108, v110
	v_add_f32_e32 v26, v105, v26
	v_exp_f32_e32 v109, v111
	v_add_f32_e32 v26, v106, v26
	v_exp_f32_e32 v110, v112
	v_add_f32_e32 v26, v107, v26
	v_exp_f32_e32 v111, v113
	v_add_f32_e32 v26, v108, v26
	v_exp_f32_e32 v112, v114
	v_add_f32_e32 v26, v109, v26
	v_exp_f32_e32 v113, v115
	v_add_f32_e32 v26, v110, v26
	v_add_f32_e32 v26, v111, v26
	v_add_f32_e32 v26, v112, v26
	v_add_f32_e32 v26, v113, v26
	v_add_f32_e32 v29, v158, v26
	v_mov_b32_e32 v26, v24
	v_cvt_pk_bf16_f32 v102, v102, v103
	v_cvt_pk_bf16_f32 v103, v104, v105
	v_cvt_pk_bf16_f32 v124, v106, v107
	v_mfma_f32_16x16x32_bf16 v[104:107], v[96:99], v[12:15], v[24:27]
	v_cvt_pk_bf16_f32 v125, v108, v109
	v_cvt_pk_bf16_f32 v126, v110, v111
	v_cvt_pk_bf16_f32 v127, v112, v113
	v_mfma_f32_16x16x32_bf16 v[104:107], v[92:95], v[16:19], v[104:107]
	v_cvt_pk_bf16_f32 v101, v30, v31
	v_mfma_f32_16x16x32_bf16 v[108:111], v[88:91], v[12:15], v[24:27]
	v_mfma_f32_16x16x32_bf16 v[108:111], v[84:87], v[16:19], v[108:111]
	s_nop 4
	v_exp_f32_e32 v30, v106
	v_exp_f32_e32 v31, v107
	v_mfma_f32_16x16x32_bf16 v[112:115], v[80:83], v[12:15], v[24:27]
	v_mfma_f32_16x16x32_bf16 v[116:119], v[72:75], v[12:15], v[24:27]
	v_exp_f32_e32 v106, v108
	v_exp_f32_e32 v107, v109
	v_exp_f32_e32 v108, v110
	v_exp_f32_e32 v25, v104
	v_exp_f32_e32 v27, v105
	v_mfma_f32_16x16x32_bf16 v[112:115], v[76:79], v[16:19], v[112:115]
	v_exp_f32_e32 v109, v111
	v_add_f32_e32 v26, 0, v25
	v_add_f32_e32 v26, v27, v26
	v_add_f32_e32 v26, v30, v26
	v_add_f32_e32 v26, v31, v26
	v_mfma_f32_16x16x32_bf16 v[116:119], v[68:71], v[16:19], v[116:119]
	v_add_f32_e32 v26, v106, v26
	s_nop 0
	v_exp_f32_e32 v110, v112
	v_add_f32_e32 v26, v107, v26
	v_exp_f32_e32 v111, v113
	v_add_f32_e32 v26, v108, v26
	v_exp_f32_e32 v112, v114
	v_add_f32_e32 v26, v109, v26
	v_exp_f32_e32 v113, v115
	v_add_f32_e32 v26, v110, v26
	v_exp_f32_e32 v114, v116
	v_add_f32_e32 v26, v111, v26
	v_exp_f32_e32 v115, v117
	v_add_f32_e32 v26, v112, v26
	v_exp_f32_e32 v116, v118
	v_add_f32_e32 v26, v113, v26
	v_exp_f32_e32 v117, v119
	v_add_f32_e32 v26, v114, v26
	v_cvt_pk_bf16_f32 v104, v25, v27
	v_lshlrev_b32_e32 v25, 1, v0
	v_lshlrev_b32_e32 v27, 1, v153
	v_add_f32_e32 v26, v115, v26
	v_add3_u32 v25, s74, v25, v27
	v_add3_u32 v27, s74, v159, v27
	v_add_f32_e32 v26, v116, v26
	v_cvt_pk_bf16_f32 v105, v30, v31
	v_add_u32_e32 v30, 0x2000, v25
	v_add_u32_e32 v31, 0x2800, v25
	v_add_u32_e32 v25, 0x3000, v25
	v_add_u32_e32 v27, 0x2000, v27
	v_add_f32_e32 v26, v117, v26
	v_cvt_pk_bf16_f32 v106, v106, v107
	v_cvt_pk_bf16_f32 v107, v108, v109
	v_cvt_pk_bf16_f32 v132, v110, v111
	v_cvt_pk_bf16_f32 v135, v116, v117
	ds_read_b64 v[108:109], v30 offset:1024
	ds_read_b64 v[110:111], v30 offset:1056
	ds_read_b64 v[116:117], v31 offset:1280
	ds_read_b64 v[118:119], v31 offset:1312
	ds_read_b64 v[128:129], v25 offset:1536
	ds_read_b64 v[130:131], v25 offset:1568
	ds_read_b64 v[164:165], v27 offset:1024
	ds_read_b64 v[166:167], v27 offset:1056
	v_cvt_pk_bf16_f32 v133, v112, v113
	v_cvt_pk_bf16_f32 v134, v114, v115
	s_waitcnt lgkmcnt(3)
	v_mfma_f32_16x16x32_bf16 v[112:115], v[108:111], v[100:103], v[60:63]
	v_add_f32_e32 v26, v157, v26
	s_waitcnt lgkmcnt(2)
	v_mfma_f32_16x16x32_bf16 v[120:123], v[116:119], v[100:103], v[52:55]
	s_waitcnt lgkmcnt(1)
	v_mfma_f32_16x16x32_bf16 v[160:163], v[128:131], v[100:103], v[44:47]
	s_waitcnt lgkmcnt(0)
	v_mfma_f32_16x16x32_bf16 v[168:171], v[164:167], v[100:103], v[36:39]
	ds_read_b64 v[100:101], v30 offset:1088
	ds_read_b64 v[102:103], v30 offset:1120
	v_mfma_f32_16x16x32_bf16 v[108:111], v[108:111], v[104:107], v[64:67]
	v_mfma_f32_16x16x32_bf16 v[116:119], v[116:119], v[104:107], v[56:59]
	v_mfma_f32_16x16x32_bf16 v[128:131], v[128:131], v[104:107], v[48:51]
	v_mfma_f32_16x16x32_bf16 v[164:167], v[164:167], v[104:107], v[40:43]
	s_waitcnt lgkmcnt(0)
	v_mfma_f32_16x16x32_bf16 v[104:107], v[100:103], v[124:127], v[112:115]
	v_mfma_f32_16x16x32_bf16 v[100:103], v[100:103], v[132:135], v[108:111]
	s_nop 2
	ds_read_b64 v[108:109], v31 offset:1344
	ds_read_b64 v[110:111], v31 offset:1376
	s_waitcnt lgkmcnt(0)
	v_mfma_f32_16x16x32_bf16 v[112:115], v[108:111], v[124:127], v[120:123]
	v_mfma_f32_16x16x32_bf16 v[108:111], v[108:111], v[132:135], v[116:119]
	s_nop 2
	ds_read_b64 v[116:117], v25 offset:1600
	ds_read_b64 v[118:119], v25 offset:1632
	s_waitcnt lgkmcnt(0)
	v_mfma_f32_16x16x32_bf16 v[120:123], v[116:119], v[124:127], v[160:163]
	s_nop 2
	ds_read_b64 v[160:161], v27 offset:1088
	ds_read_b64 v[162:163], v27 offset:1120
	v_mov_b32_e32 v25, v28
	v_mov_b32_e32 v27, v24
	v_mfma_f32_16x16x32_bf16 v[116:119], v[116:119], v[132:135], v[128:131]
	s_waitcnt lgkmcnt(0)
	v_mfma_f32_16x16x32_bf16 v[128:131], v[160:163], v[124:127], v[168:171]
	v_mfma_f32_16x16x32_bf16 v[124:127], v[160:163], v[132:135], v[164:167]

; DI f32x4 mfma16(bf16x8 a, bf16x8 b, f32x4 c) { return __builtin_amdgcn_mfma_f32_16x16x32_bf16(a, b, c, 0, 0, 0); }
; template <int MODE, bool MASKED, class MaskF>
; DI void flash_tile(const u16* sK, const u16* sV, const bf16x8 (&qf)[2][2], f32x4 (&O)[2][4], float (&m)[2], float (&l)[2],
;                    float (&ps)[4][4], MaskF ok, bool sel, int lane) {
;     ...
;   for (int qt = 0; qt < 2; ++qt) {
;     f32x4 s[4];
;     const float sinit = (MODE == 3) ? ((MASKED || sel) ? m[qt] : -1e30f) : 0.f;
; #pragma unroll
;     for (int kt = 0; kt < 4; ++kt) {
;       s[kt] = f32x4{sinit, sinit, sinit, sinit};
; #pragma unroll
;       for (int ks = 0; ks < 2; ++ks) s[kt] = mfma16(kf[kt][ks], qf[qt][ks], s[kt]);
;     }
;     float pr[4][4];
;     if (MODE == 3) {
;       float rs = 0.f;
; #pragma unroll
;       for (int kt = 0; kt < 4; ++kt)
; #pragma unroll
;         for (int i = 0; i < 4; ++i) {
;           float pv = __builtin_amdgcn_exp2f(s[kt][i]);
;           if (MASKED) pv = ok(kt, i) ? pv : 0.f;
;           pr[kt][i] = pv;
;           rs += pv;
;         }
;       l[qt] += rs;
;     } else {
;     float mx = -1e30f;
; #pragma unroll
;     for (int kt = 0; kt < 4; ++kt)
; #pragma unroll
;       for (int i = 0; i < 4; ++i) {
;         if (MASKED) s[kt][i] = ok(kt, i) ? s[kt][i] : -1e30f;
;         mx = fmaxf(mx, s[kt][i]);
;       }
;     if (!MASKED) mx = sel ? mx : -1e30f;
;     if (MODE == 1) {
;       const float mm = m[qt], il = l[qt];
; #pragma unroll
;       for (int kt = 0; kt < 4; ++kt)
; #pragma unroll
;         for (int i = 0; i < 4; ++i) {
;           const float pv = (s[kt][i] > -1e29f) ? __builtin_amdgcn_exp2f(s[kt][i] - mm) * il : 0.f;
;           pr[kt][i] = pv;
;           ps[kt][i] += pv;
;         }
;     } else {
;       mx = fmaxf(mx, __shfl_xor(mx, 16));
;       mx = fmaxf(mx, __shfl_xor(mx, 32));
;       const float mnew = fmaxf(m[qt], mx);
;       const float alpha = __builtin_amdgcn_exp2f(m[qt] - mnew);
; DI void nsa_item(int wv0, PP p, int item, unsigned char* smem) {
;     ...
;         auto ok = [&](int kt, int ii) {
;           const int kp = j * 64 + 16 * kt + 4 * lg + ii;
;           return kp <= tq && kp > tq - 512;
.LBB0_909:
	s_andn2_b64 vcc, exec, s[2:3]
	s_cbranch_vccnz .LBB0_913
	v_subrev_u32_e32 v171, 51, v156
	v_subrev_u32_e32 v170, 49, v156
	v_subrev_u32_e32 v169, 48, v156
	v_subrev_u32_e32 v168, 35, v156
	v_subrev_u32_e32 v167, 34, v156
	v_subrev_u32_e32 v166, 33, v156
	v_subrev_u32_e32 v165, 32, v156
	v_subrev_u32_e32 v164, 19, v156
	v_subrev_u32_e32 v163, 18, v156
	v_subrev_u32_e32 v162, 17, v156
	v_add_u32_e32 v161, -16, v156
	v_add_u32_e32 v160, -3, v156
	v_add_u32_e32 v159, -2, v156
	v_add_u32_e32 v135, -1, v156
	s_and_b64 vcc, exec, s[90:91]
	v_cmp_le_i32_e64 s[30:31], v156, v151
	v_cmp_gt_i32_e64 s[34:35], v156, v3
	v_cmp_le_i32_e64 s[64:65], v171, v151
	v_cmp_gt_i32_e64 s[66:67], v171, v3
	v_cmp_lt_i32_e64 s[2:3], v171, v151
	v_cmp_ge_i32_e64 s[62:63], v171, v3
	v_cmp_le_i32_e64 s[4:5], v170, v151
	v_cmp_gt_i32_e64 s[60:61], v170, v3
	v_cmp_le_i32_e64 s[6:7], v169, v151
	v_cmp_gt_i32_e64 s[58:59], v169, v3
	v_cmp_le_i32_e64 s[8:9], v168, v151
	v_cmp_gt_i32_e64 s[56:57], v168, v3
	v_cmp_le_i32_e64 s[10:11], v167, v151
	v_cmp_gt_i32_e64 s[54:55], v167, v3
	v_cmp_le_i32_e64 s[12:13], v166, v151
	v_cmp_gt_i32_e64 s[52:53], v166, v3
	v_cmp_le_i32_e64 s[14:15], v165, v151
	v_cmp_gt_i32_e64 s[50:51], v165, v3
	v_cmp_le_i32_e64 s[16:17], v164, v151
	v_cmp_gt_i32_e64 s[48:49], v164, v3
	v_cmp_le_i32_e64 s[18:19], v163, v151
	v_cmp_gt_i32_e64 s[46:47], v163, v3
	v_cmp_le_i32_e64 s[20:21], v162, v151
	v_cmp_gt_i32_e64 s[42:43], v162, v3
	v_cmp_le_i32_e64 s[22:23], v161, v151
	v_cmp_gt_i32_e64 s[44:45], v161, v3
	v_cmp_le_i32_e64 s[24:25], v160, v151
	v_cmp_gt_i32_e64 s[38:39], v160, v3
	v_cmp_le_i32_e64 s[26:27], v159, v151
	v_cmp_gt_i32_e64 s[40:41], v159, v3
	v_cmp_le_i32_e64 s[28:29], v135, v151
	v_cmp_gt_i32_e64 s[36:37], v135, v3
	v_lshlrev_b32_e32 v134, 1, v0
	v_lshlrev_b32_e32 v132, 1, v153
	v_lshlrev_b32_e32 v133, 1, v2
	s_cbranch_vccz .LBB0_920
	s_waitcnt lgkmcnt(7)
	v_mfma_f32_16x16x32_bf16 v[100:103], v[96:99], v[4:7], 0
	s_and_b64 vcc, s[64:65], s[66:67]
	s_and_b64 s[2:3], s[2:3], s[62:63]
	s_and_b64 s[4:5], s[4:5], s[60:61]
	s_waitcnt lgkmcnt(6)
	v_mfma_f32_16x16x32_bf16 v[100:103], v[92:95], v[8:11], v[100:103]
	s_and_b64 s[6:7], s[6:7], s[58:59]
	s_and_b64 s[8:9], s[8:9], s[56:57]
	s_and_b64 s[10:11], s[10:11], s[54:55]
	s_waitcnt lgkmcnt(5)
	v_mfma_f32_16x16x32_bf16 v[104:107], v[88:91], v[4:7], 0
	s_and_b64 s[12:13], s[12:13], s[52:53]
	s_nop 1
	v_cndmask_b32_e32 v26, v148, v100, vcc
	v_cndmask_b32_e64 v27, v148, v101, s[2:3]
	v_cndmask_b32_e64 v29, v148, v102, s[4:5]
	v_cndmask_b32_e64 v30, v148, v103, s[6:7]
	s_waitcnt lgkmcnt(4)
	v_mfma_f32_16x16x32_bf16 v[100:103], v[84:87], v[8:11], v[104:107]
	s_and_b64 s[14:15], s[14:15], s[50:51]
	v_max3_f32 v25, v26, s1, v27
	v_max3_f32 v25, v25, v29, v30
	s_waitcnt lgkmcnt(3)
	v_mfma_f32_16x16x32_bf16 v[104:107], v[80:83], v[4:7], 0
	s_and_b64 s[16:17], s[16:17], s[48:49]
	s_nop 1
	v_cndmask_b32_e64 v31, v148, v100, s[8:9]
	v_cndmask_b32_e64 v108, v148, v101, s[10:11]
	v_cndmask_b32_e64 v109, v148, v102, s[12:13]
	v_cndmask_b32_e64 v110, v148, v103, s[14:15]
	s_waitcnt lgkmcnt(1)
	v_mfma_f32_16x16x32_bf16 v[100:103], v[72:75], v[4:7], 0
	v_max3_f32 v25, v25, v31, v108
	s_and_b64 s[18:19], s[18:19], s[46:47]
	v_max3_f32 v25, v25, v109, v110
	v_mfma_f32_16x16x32_bf16 v[104:107], v[76:79], v[8:11], v[104:107]
	s_and_b64 s[20:21], s[20:21], s[42:43]
	s_and_b64 s[22:23], s[22:23], s[44:45]
	s_and_b64 s[24:25], s[24:25], s[38:39]
	s_waitcnt lgkmcnt(0)
	v_mfma_f32_16x16x32_bf16 v[100:103], v[68:71], v[8:11], v[100:103]
	s_and_b64 s[26:27], s[26:27], s[40:41]
	s_nop 1
	v_cndmask_b32_e64 v104, v148, v104, s[16:17]
	v_cndmask_b32_e64 v105, v148, v105, s[18:19]
	v_max3_f32 v25, v25, v104, v105
	v_cndmask_b32_e64 v106, v148, v106, s[20:21]
	v_cndmask_b32_e64 v107, v148, v107, s[22:23]
	v_max3_f32 v25, v25, v106, v107
	v_cndmask_b32_e64 v100, v148, v100, s[24:25]
	v_cndmask_b32_e64 v101, v148, v101, s[26:27]
	s_and_b64 s[28:29], s[28:29], s[36:37]
	s_and_b64 s[30:31], s[30:31], s[34:35]
	v_max3_f32 v25, v25, v100, v101
	v_cndmask_b32_e64 v112, v148, v102, s[28:29]
	v_cndmask_b32_e64 v116, v148, v103, s[30:31]
	v_max3_f32 v25, v25, v112, v116
	ds_bpermute_b32 v102, v144, v25
	v_cmp_lt_f32_e64 s[34:35], s82, v26
	v_mfma_f32_16x16x32_bf16 v[124:127], v[72:75], v[12:15], 0
	s_waitcnt lgkmcnt(0)
	v_max_f32_e32 v102, v102, v102
	v_max_f32_e32 v25, v25, v102
	ds_bpermute_b32 v102, v145, v25
	v_mfma_f32_16x16x32_bf16 v[124:127], v[68:71], v[16:19], v[124:127]
	s_waitcnt lgkmcnt(0)
; template <int MODE, bool MASKED, class MaskF>
; DI void flash_tile(const u16* sK, const u16* sV, const bf16x8 (&qf)[2][2], f32x4 (&O)[2][4], float (&m)[2], float (&l)[2],
;                    float (&ps)[4][4], MaskF ok, bool sel, int lane) {
;     ...
;     } else {
;       mx = fmaxf(mx, __shfl_xor(mx, 16));
;       mx = fmaxf(mx, __shfl_xor(mx, 32));
;       const float mnew = fmaxf(m[qt], mx);
;       const float alpha = __builtin_amdgcn_exp2f(m[qt] - mnew);
;       m[qt] = mnew;
;       float rs = 0.f;
;       if (MASKED) {
; #pragma unroll
;         for (int kt = 0; kt < 4; ++kt)
; #pragma unroll
;           for (int i = 0; i < 4; ++i) {
;             const float pv = (s[kt][i] > -1e29f) ? __builtin_amdgcn_exp2f(s[kt][i] - mnew) : 0.f;
;             pr[kt][i] = pv;
;             rs += pv;
;           }
;       } else {
;         const float me = sel ? mnew : 1e30f;
; #pragma unroll
;         for (int kt = 0; kt < 4; ++kt)
; #pragma unroll
;           for (int i = 0; i < 4; ++i) {
;             const float pv = __builtin_amdgcn_exp2f(s[kt][i] - me);
;             pr[kt][i] = pv;
;             rs += pv;
;           }
;       }
;       l[qt] = l[qt] * alpha + rs;
;       if (MODE == 2) {
; #pragma unroll
;         for (int dt = 0; dt < 4; ++dt) O[qt][dt] *= alpha;
;       }
;     }
;     }
;     if (MODE != 0) {
; #pragma unroll
;       for (int ks2 = 0; ks2 < 2; ++ks2) {
;         pf[qt][ks2].u[0] = pk2(pr[2 * ks2][0], pr[2 * ks2][1]);
;         pf[qt][ks2].u[1] = pk2(pr[2 * ks2][2], pr[2 * ks2][3]);
;         pf[qt][ks2].u[2] = pk2(pr[2 * ks2 + 1][0], pr[2 * ks2 + 1][1]);
;         pf[qt][ks2].u[3] = pk2(pr[2 * ks2 + 1][2], pr[2 * ks2 + 1][3]);
;       }
;     }
	v_max3_f32 v25, v28, v25, v102
	v_sub_f32_e32 v102, v26, v25
	v_exp_f32_e32 v102, v102
	v_sub_f32_e32 v103, v27, v25
	v_exp_f32_e32 v103, v103
	v_sub_f32_e32 v113, v28, v25
	v_cndmask_b32_e64 v172, 0, v102, s[34:35]
	v_sub_f32_e32 v102, v29, v25
	v_exp_f32_e32 v102, v102
	v_cmp_lt_f32_e64 s[34:35], s82, v27
	v_add_f32_e32 v26, 0, v172
	v_cndmask_b32_e64 v188, v148, v124, s[24:25]
	v_cndmask_b32_e64 v27, 0, v103, s[34:35]
	v_sub_f32_e32 v103, v30, v25
	v_exp_f32_e32 v103, v103
	v_cmp_lt_f32_e64 s[34:35], s82, v29
	v_sub_f32_e32 v29, v31, v25
	v_exp_f32_e32 v29, v29
	v_cndmask_b32_e64 v173, 0, v102, s[34:35]
	v_sub_f32_e32 v102, v108, v25
	v_exp_f32_e32 v102, v102
	v_cmp_lt_f32_e64 s[34:35], s82, v30
	v_add_f32_e32 v26, v27, v26
	v_add_f32_e32 v26, v173, v26
	v_cndmask_b32_e64 v30, 0, v103, s[34:35]
	v_cmp_lt_f32_e64 s[34:35], s82, v31
	v_add_f32_e32 v26, v30, v26
	v_cndmask_b32_e64 v189, v148, v125, s[26:27]
	v_cndmask_b32_e64 v31, 0, v29, s[34:35]
	v_cmp_lt_f32_e64 s[34:35], s82, v108
	v_sub_f32_e32 v29, v109, v25
	v_exp_f32_e32 v29, v29
	v_cndmask_b32_e64 v174, 0, v102, s[34:35]
	v_sub_f32_e32 v102, v110, v25
	v_exp_f32_e32 v102, v102
	v_cmp_lt_f32_e64 s[34:35], s82, v109
	v_add_f32_e32 v26, v31, v26
	v_add_f32_e32 v26, v174, v26
	v_cndmask_b32_e64 v175, 0, v29, s[34:35]
	v_cmp_lt_f32_e64 s[34:35], s82, v110
	v_sub_f32_e32 v29, v104, v25
	v_exp_f32_e32 v29, v29
	v_cndmask_b32_e64 v176, 0, v102, s[34:35]
	v_sub_f32_e32 v102, v105, v25
	v_exp_f32_e32 v102, v102
	v_cmp_lt_f32_e64 s[34:35], s82, v104
	v_add_f32_e32 v26, v175, v26
	v_add_f32_e32 v26, v176, v26
	v_cndmask_b32_e64 v177, 0, v29, s[34:35]
	v_cmp_lt_f32_e64 s[34:35], s82, v105
	v_sub_f32_e32 v29, v106, v25
	v_exp_f32_e32 v29, v29
	v_cndmask_b32_e64 v178, 0, v102, s[34:35]
	v_sub_f32_e32 v102, v107, v25
	v_exp_f32_e32 v102, v102
	v_cmp_lt_f32_e64 s[34:35], s82, v106
	v_add_f32_e32 v26, v177, v26
	v_add_f32_e32 v26, v178, v26
	v_cndmask_b32_e64 v179, 0, v29, s[34:35]
	v_cmp_lt_f32_e64 s[34:35], s82, v107
	v_sub_f32_e32 v29, v100, v25
	v_exp_f32_e32 v29, v29
	v_cndmask_b32_e64 v180, 0, v102, s[34:35]
	v_sub_f32_e32 v102, v101, v25
	v_exp_f32_e32 v102, v102
	v_cmp_lt_f32_e64 s[34:35], s82, v100
	v_add_f32_e32 v26, v179, v26
	v_add_f32_e32 v26, v180, v26
	v_cndmask_b32_e64 v181, 0, v29, s[34:35]
	v_cmp_lt_f32_e64 s[34:35], s82, v101
	v_sub_f32_e32 v29, v112, v25
	v_exp_f32_e32 v29, v29
	v_cndmask_b32_e64 v182, 0, v102, s[34:35]
	v_mfma_f32_16x16x32_bf16 v[100:103], v[96:99], v[12:15], 0
	v_add_f32_e32 v26, v181, v26
	v_cmp_lt_f32_e64 s[34:35], s82, v112
	v_add_f32_e32 v26, v182, v26
	v_mfma_f32_16x16x32_bf16 v[108:111], v[92:95], v[16:19], v[100:103]
	v_cndmask_b32_e64 v183, 0, v29, s[34:35]
	v_add_f32_e32 v29, v183, v26
	v_sub_f32_e32 v26, v116, v25
	v_mfma_f32_16x16x32_bf16 v[100:103], v[88:91], v[12:15], 0
	v_exp_f32_e32 v104, v26
	v_exp_f32_e32 v26, v113
	v_cmp_lt_f32_e64 s[34:35], s82, v116
	v_mfma_f32_16x16x32_bf16 v[112:115], v[84:87], v[16:19], v[100:103]
	v_cndmask_b32_e64 v185, v148, v109, s[2:3]
	v_cndmask_b32_e64 v184, 0, v104, s[34:35]
	v_add_f32_e32 v29, v184, v29
	v_mfma_f32_16x16x32_bf16 v[100:103], v[80:83], v[12:15], 0
	v_fmac_f32_e32 v29, v158, v26
	v_pk_mul_f32 v[118:119], v[62:63], v[26:27] op_sel_hi:[1,0]
	v_pk_mul_f32 v[116:117], v[60:61], v[26:27] op_sel_hi:[1,0]
	v_mfma_f32_16x16x32_bf16 v[120:123], v[76:79], v[16:19], v[100:103]
	v_mul_f32_e64 v130, v54, v26
	v_mul_f32_e64 v131, v55, v26
	v_pk_mul_f32 v[128:129], v[52:53], v[26:27] op_sel_hi:[1,0]
	v_pk_mul_f32 v[106:107], v[46:47], v[26:27] op_sel_hi:[1,0]
	v_pk_mul_f32 v[104:105], v[44:45], v[26:27] op_sel_hi:[1,0]
	v_pk_mul_f32 v[102:103], v[38:39], v[26:27] op_sel_hi:[1,0]
	v_pk_mul_f32 v[100:101], v[36:37], v[26:27] op_sel_hi:[1,0]
	v_cndmask_b32_e32 v26, v148, v108, vcc
	v_cndmask_b32_e64 v186, v148, v110, s[4:5]
	v_cndmask_b32_e64 v187, v148, v111, s[6:7]
	v_max3_f32 v108, v26, s1, v185
	v_cndmask_b32_e64 v112, v148, v112, s[8:9]
	v_cndmask_b32_e64 v113, v148, v113, s[10:11]
	v_max3_f32 v108, v108, v186, v187
	v_cndmask_b32_e64 v114, v148, v114, s[12:13]
	v_cndmask_b32_e64 v115, v148, v115, s[14:15]
	v_max3_f32 v108, v108, v112, v113
	v_cndmask_b32_e64 v120, v148, v120, s[16:17]
	v_cndmask_b32_e64 v121, v148, v121, s[18:19]
	v_max3_f32 v108, v108, v114, v115
	v_cndmask_b32_e64 v122, v148, v122, s[20:21]
	v_cndmask_b32_e64 v123, v148, v123, s[22:23]
	v_max3_f32 v108, v108, v120, v121
	v_max3_f32 v108, v108, v122, v123
	v_cndmask_b32_e64 v192, v148, v126, s[28:29]
	v_cndmask_b32_e64 v196, v148, v127, s[30:31]
	v_max3_f32 v108, v108, v188, v189
	v_max3_f32 v108, v108, v192, v196
	ds_bpermute_b32 v109, v144, v108
	v_cvt_pk_bf16_f32 v124, v177, v178
	v_cvt_pk_bf16_f32 v110, v31, v174
	v_cmp_lt_f32_e32 vcc, s82, v26
	v_cvt_pk_bf16_f32 v125, v179, v180
	s_waitcnt lgkmcnt(0)
	v_max_f32_e32 v109, v109, v109
	v_max_f32_e32 v177, v108, v109
	ds_bpermute_b32 v178, v145, v177
	v_cvt_pk_bf16_f32 v108, v172, v27
	v_cvt_pk_bf16_f32 v109, v173, v30
	v_add3_u32 v180, s74, v134, v132
	v_add_u32_e32 v208, 0x2000, v180
	s_waitcnt lgkmcnt(0)
; DI f32x4 mfma16(bf16x8 a, bf16x8 b, f32x4 c) { return __builtin_amdgcn_mfma_f32_16x16x32_bf16(a, b, c, 0, 0, 0); }
; template <int MODE, bool MASKED, class MaskF>
; DI void flash_tile(const u16* sK, const u16* sV, const bf16x8 (&qf)[2][2], f32x4 (&O)[2][4], float (&m)[2], float (&l)[2],
;                    float (&ps)[4][4], MaskF ok, bool sel, int lane) {
;     ...
;     } else {
;       mx = fmaxf(mx, __shfl_xor(mx, 16));
;       mx = fmaxf(mx, __shfl_xor(mx, 32));
;       const float mnew = fmaxf(m[qt], mx);
;       const float alpha = __builtin_amdgcn_exp2f(m[qt] - mnew);
;       m[qt] = mnew;
;       float rs = 0.f;
;       if (MASKED) {
; #pragma unroll
;         for (int kt = 0; kt < 4; ++kt)
; #pragma unroll
;           for (int i = 0; i < 4; ++i) {
;             const float pv = (s[kt][i] > -1e29f) ? __builtin_amdgcn_exp2f(s[kt][i] - mnew) : 0.f;
;             pr[kt][i] = pv;
;             rs += pv;
;           }
;       } else {
;         const float me = sel ? mnew : 1e30f;
; #pragma unroll
;         for (int kt = 0; kt < 4; ++kt)
; #pragma unroll
;           for (int i = 0; i < 4; ++i) {
;             const float pv = __builtin_amdgcn_exp2f(s[kt][i] - me);
;             pr[kt][i] = pv;
;             rs += pv;
;           }
;       }
;       l[qt] = l[qt] * alpha + rs;
;       if (MODE == 2) {
; #pragma unroll
;         for (int dt = 0; dt < 4; ++dt) O[qt][dt] *= alpha;
;       }
;     }
;     }
;     if (MODE != 0) {
; #pragma unroll
;       for (int ks2 = 0; ks2 < 2; ++ks2) {
;         pf[qt][ks2].u[0] = pk2(pr[2 * ks2][0], pr[2 * ks2][1]);
;         pf[qt][ks2].u[1] = pk2(pr[2 * ks2][2], pr[2 * ks2][3]);
;         pf[qt][ks2].u[2] = pk2(pr[2 * ks2 + 1][0], pr[2 * ks2 + 1][1]);
;         pf[qt][ks2].u[3] = pk2(pr[2 * ks2 + 1][2], pr[2 * ks2 + 1][3]);
;       }
;     }
;   }
;   if (MODE != 0) {
; #pragma unroll
;     for (int ks2 = 0; ks2 < 2; ++ks2) {
; #pragma unroll
;       for (int dt = 0; dt < 4; ++dt) {
;         union { uint2 h[2]; bf16x8 v; } vf;
;         vf.h[0] = *(const uint2*)(sV + (16 * dt + l15) * 72 + 32 * ks2 + 4 * lg);
;         vf.h[1] = *(const uint2*)(sV + (16 * dt + l15) * 72 + 32 * ks2 + 16 + 4 * lg);
;         O[0][dt] = mfma16(vf.v, pf[0][ks2].v, O[0][dt]);
;         O[1][dt] = mfma16(vf.v, pf[1][ks2].v, O[1][dt]);
;       }
;     }
	v_max3_f32 v27, v24, v177, v178
	v_sub_f32_e32 v31, v26, v27
	v_exp_f32_e32 v31, v31
	v_sub_f32_e32 v172, v185, v27
	v_exp_f32_e32 v172, v172
	v_sub_f32_e32 v173, v187, v27
	v_cndmask_b32_e32 v26, 0, v31, vcc
	v_cmp_lt_f32_e32 vcc, s82, v185
	v_exp_f32_e32 v173, v173
	v_add_f32_e32 v31, 0, v26
	v_cndmask_b32_e32 v197, 0, v172, vcc
	v_sub_f32_e32 v172, v186, v27
	v_exp_f32_e32 v172, v172
	v_cmp_lt_f32_e32 vcc, s82, v186
	v_cvt_pk_bf16_f32 v111, v175, v176
	v_sub_f32_e32 v30, v24, v27
	v_cndmask_b32_e32 v198, 0, v172, vcc
	v_sub_f32_e32 v172, v112, v27
	v_cmp_lt_f32_e32 vcc, s82, v187
	v_exp_f32_e32 v172, v172
	v_cvt_pk_bf16_f32 v126, v181, v182
	v_cndmask_b32_e32 v199, 0, v173, vcc
	v_sub_f32_e32 v173, v113, v27
	v_exp_f32_e32 v173, v173
	v_cmp_lt_f32_e32 vcc, s82, v112
	v_sub_f32_e32 v112, v114, v27
	v_exp_f32_e32 v112, v112
	v_cndmask_b32_e32 v200, 0, v172, vcc
	v_cmp_lt_f32_e32 vcc, s82, v113
	v_sub_f32_e32 v113, v115, v27
	v_exp_f32_e32 v113, v113
	v_cndmask_b32_e32 v201, 0, v173, vcc
	v_cmp_lt_f32_e32 vcc, s82, v114
	v_cvt_pk_bf16_f32 v172, v26, v197
	v_add_u32_e32 v26, 0x2800, v180
	v_cndmask_b32_e32 v202, 0, v112, vcc
	v_sub_f32_e32 v112, v120, v27
	v_cmp_lt_f32_e32 vcc, s82, v115
	v_exp_f32_e32 v112, v112
	ds_read_b64 v[176:177], v26 offset:1280
	ds_read_b64 v[178:179], v26 offset:1312
	v_cndmask_b32_e32 v203, 0, v113, vcc
	v_sub_f32_e32 v113, v121, v27
	v_exp_f32_e32 v113, v113
	v_cmp_lt_f32_e32 vcc, s82, v120
	v_exp_f32_e32 v30, v30
	v_cvt_pk_bf16_f32 v127, v183, v184
	v_cndmask_b32_e32 v204, 0, v112, vcc
	v_sub_f32_e32 v112, v122, v27
	v_cmp_lt_f32_e32 vcc, s82, v121
	v_exp_f32_e32 v112, v112
	v_cvt_pk_bf16_f32 v173, v198, v199
	v_cndmask_b32_e32 v205, 0, v113, vcc
	v_sub_f32_e32 v113, v123, v27
	v_exp_f32_e32 v113, v113
	v_cmp_lt_f32_e32 vcc, s82, v122
	v_cvt_pk_bf16_f32 v174, v200, v201
	v_cvt_pk_bf16_f32 v175, v202, v203
	v_cndmask_b32_e32 v206, 0, v112, vcc
	v_sub_f32_e32 v112, v188, v27
	v_cmp_lt_f32_e32 vcc, s82, v123
	v_exp_f32_e32 v120, v112
	v_pk_mul_f32 v[122:123], v[66:67], v[30:31] op_sel_hi:[1,0]
	v_cndmask_b32_e32 v207, 0, v113, vcc
	ds_read_b64 v[112:113], v208 offset:1024
	ds_read_b64 v[114:115], v208 offset:1056
	v_cmp_lt_f32_e32 vcc, s82, v188
	v_add_u32_e32 v211, 0x3000, v180
	v_pk_mul_f32 v[182:183], v[58:59], v[30:31] op_sel_hi:[1,0]
	v_cndmask_b32_e32 v209, 0, v120, vcc
	v_sub_f32_e32 v120, v189, v27
	v_exp_f32_e32 v181, v120
	v_cmp_lt_f32_e32 vcc, s82, v189
	v_pk_mul_f32 v[120:121], v[64:65], v[30:31] op_sel_hi:[1,0]
	s_waitcnt lgkmcnt(0)
	v_mfma_f32_16x16x32_bf16 v[116:119], v[112:115], v[108:111], v[116:119]
	v_cndmask_b32_e32 v210, 0, v181, vcc
	v_pk_mul_f32 v[180:181], v[56:57], v[30:31] op_sel_hi:[1,0]
	v_sub_f32_e32 v188, v192, v27
	v_mfma_f32_16x16x32_bf16 v[112:115], v[112:115], v[172:175], v[120:123]
	v_exp_f32_e32 v193, v188
	v_cmp_lt_f32_e32 vcc, s82, v192
	s_nop 0
	ds_read_b64 v[120:121], v211 offset:1536
	ds_read_b64 v[122:123], v211 offset:1568
	v_mfma_f32_16x16x32_bf16 v[128:131], v[176:179], v[108:111], v[128:131]
	v_cndmask_b32_e32 v213, 0, v193, vcc
	v_cmp_lt_f32_e32 vcc, s82, v196
	v_mfma_f32_16x16x32_bf16 v[176:179], v[176:179], v[172:175], v[180:183]
	s_nop 2
	v_add3_u32 v180, s74, v133, v132
	v_add_u32_e32 v212, 0x2000, v180
	ds_read_b64 v[180:181], v212 offset:1024
	ds_read_b64 v[182:183], v212 offset:1056
	s_waitcnt lgkmcnt(1)
	v_mfma_f32_16x16x32_bf16 v[184:187], v[120:123], v[108:111], v[104:107]
	s_nop 2
	v_mul_f32_e64 v106, v50, v30
	v_mul_f32_e64 v107, v51, v30
	v_pk_mul_f32 v[104:105], v[48:49], v[30:31] op_sel_hi:[1,0]
	s_waitcnt lgkmcnt(0)
	v_mfma_f32_16x16x32_bf16 v[192:195], v[180:183], v[108:111], v[100:103]
	s_nop 2
	ds_read_b64 v[100:101], v208 offset:1088
	ds_read_b64 v[102:103], v208 offset:1120
	v_mfma_f32_16x16x32_bf16 v[188:191], v[120:123], v[172:175], v[104:107]
	s_nop 2
	v_sub_f32_e32 v104, v196, v27
	v_exp_f32_e32 v108, v104
	v_pk_mul_f32 v[106:107], v[42:43], v[30:31] op_sel_hi:[1,0]
	v_pk_mul_f32 v[104:105], v[40:41], v[30:31] op_sel_hi:[1,0]
	v_cndmask_b32_e32 v196, 0, v108, vcc
	ds_read_b64 v[108:109], v26 offset:1344
	ds_read_b64 v[110:111], v26 offset:1376
	v_add_f32_e32 v26, v197, v31
	v_add_f32_e32 v26, v198, v26
	v_add_f32_e32 v26, v199, v26
	v_add_f32_e32 v26, v200, v26
	v_add_f32_e32 v26, v201, v26
	v_mfma_f32_16x16x32_bf16 v[172:175], v[180:183], v[172:175], v[104:107]
	v_cvt_pk_bf16_f32 v180, v204, v205
	v_cvt_pk_bf16_f32 v181, v206, v207
	v_cvt_pk_bf16_f32 v182, v209, v210
	v_cvt_pk_bf16_f32 v183, v213, v196
	v_add_f32_e32 v26, v202, v26
	s_waitcnt lgkmcnt(1)
	v_mfma_f32_16x16x32_bf16 v[104:107], v[100:103], v[124:127], v[116:119]
	v_add_f32_e32 v26, v203, v26
	v_add_f32_e32 v26, v204, v26
	v_add_f32_e32 v26, v205, v26
	v_mfma_f32_16x16x32_bf16 v[100:103], v[100:103], v[180:183], v[112:115]
	ds_read_b64 v[116:117], v211 offset:1600
	ds_read_b64 v[118:119], v211 offset:1632
	v_add_f32_e32 v26, v206, v26
	v_add_f32_e32 v26, v207, v26
	s_waitcnt lgkmcnt(1)
	v_mfma_f32_16x16x32_bf16 v[112:115], v[108:111], v[124:127], v[128:131]
	v_add_f32_e32 v26, v209, v26
	v_add_f32_e32 v26, v210, v26
	v_add_f32_e32 v26, v213, v26
	v_mfma_f32_16x16x32_bf16 v[108:111], v[108:111], v[180:183], v[176:179]
	v_add_f32_e32 v26, v196, v26
	v_fmac_f32_e32 v26, v157, v30
	s_nop 0
	ds_read_b64 v[176:177], v212 offset:1088
	ds_read_b64 v[178:179], v212 offset:1120
	s_waitcnt lgkmcnt(1)
	v_mfma_f32_16x16x32_bf16 v[120:123], v[116:119], v[124:127], v[184:187]
	v_mfma_f32_16x16x32_bf16 v[116:119], v[116:119], v[180:183], v[188:191]
	s_waitcnt lgkmcnt(0)
	v_mfma_f32_16x16x32_bf16 v[128:131], v[176:179], v[124:127], v[192:195]
	v_mfma_f32_16x16x32_bf16 v[124:127], v[176:179], v[180:183], v[172:175]
	s_cbranch_execnz .LBB0_913
; DI f32x4 mfma16(bf16x8 a, bf16x8 b, f32x4 c) { return __builtin_amdgcn_mfma_f32_16x16x32_bf16(a, b, c, 0, 0, 0); }
; template <int MODE, bool MASKED, class MaskF>
; DI void flash_tile(const u16* sK, const u16* sV, const bf16x8 (&qf)[2][2], f32x4 (&O)[2][4], float (&m)[2], float (&l)[2],
;                    float (&ps)[4][4], MaskF ok, bool sel, int lane) {
;     ...
;   for (int qt = 0; qt < 2; ++qt) {
;     f32x4 s[4];
;     const float sinit = (MODE == 3) ? ((MASKED || sel) ? m[qt] : -1e30f) : 0.f;
; #pragma unroll
;     for (int kt = 0; kt < 4; ++kt) {
;       s[kt] = f32x4{sinit, sinit, sinit, sinit};
; #pragma unroll
;       for (int ks = 0; ks < 2; ++ks) s[kt] = mfma16(kf[kt][ks], qf[qt][ks], s[kt]);
;     }
;     float pr[4][4];
;     if (MODE == 3) {
;       float rs = 0.f;
; #pragma unroll
;       for (int kt = 0; kt < 4; ++kt)
; #pragma unroll
;         for (int i = 0; i < 4; ++i) {
;           float pv = __builtin_amdgcn_exp2f(s[kt][i]);
;           if (MASKED) pv = ok(kt, i) ? pv : 0.f;
;           pr[kt][i] = pv;
;           rs += pv;
;         }
;       l[qt] += rs;
;     ...
;     if (MODE != 0) {
; #pragma unroll
;       for (int ks2 = 0; ks2 < 2; ++ks2) {
;         pf[qt][ks2].u[0] = pk2(pr[2 * ks2][0], pr[2 * ks2][1]);
;         pf[qt][ks2].u[1] = pk2(pr[2 * ks2][2], pr[2 * ks2][3]);
;         pf[qt][ks2].u[2] = pk2(pr[2 * ks2 + 1][0], pr[2 * ks2 + 1][1]);
;         pf[qt][ks2].u[3] = pk2(pr[2 * ks2 + 1][2], pr[2 * ks2 + 1][3]);
;       }
;     }
;   }
;   if (MODE != 0) {
; #pragma unroll
;     for (int ks2 = 0; ks2 < 2; ++ks2) {
; #pragma unroll
;       for (int dt = 0; dt < 4; ++dt) {
;         union { uint2 h[2]; bf16x8 v; } vf;
;         vf.h[0] = *(const uint2*)(sV + (16 * dt + l15) * 72 + 32 * ks2 + 4 * lg);
;         vf.h[1] = *(const uint2*)(sV + (16 * dt + l15) * 72 + 32 * ks2 + 16 + 4 * lg);
;         O[0][dt] = mfma16(vf.v, pf[0][ks2].v, O[0][dt]);
;         O[1][dt] = mfma16(vf.v, pf[1][ks2].v, O[1][dt]);
;       }
;     }
.LBB0_912:
	v_mov_b32_e32 v29, v28
	v_mov_b32_e32 v30, v28
	v_mov_b32_e32 v31, v28
	v_cmp_le_i32_e32 vcc, v171, v151
	v_cmp_gt_i32_e64 s[2:3], v171, v3
	s_waitcnt lgkmcnt(7)
	v_mfma_f32_16x16x32_bf16 v[100:103], v[96:99], v[4:7], v[28:31]
	v_cmp_lt_i32_e64 s[4:5], v171, v151
	s_and_b64 s[24:25], vcc, s[2:3]
	v_cmp_ge_i32_e32 vcc, v171, v3
	s_waitcnt lgkmcnt(6)
	v_mfma_f32_16x16x32_bf16 v[100:103], v[92:95], v[8:11], v[100:103]
	s_and_b64 s[22:23], s[4:5], vcc
	v_cmp_le_i32_e32 vcc, v170, v151
	v_cmp_gt_i32_e64 s[2:3], v170, v3
	s_waitcnt lgkmcnt(5)
	v_mfma_f32_16x16x32_bf16 v[104:107], v[88:91], v[4:7], v[28:31]
	s_and_b64 s[26:27], vcc, s[2:3]
	s_nop 1
	v_exp_f32_e32 v26, v101
	v_cmp_le_i32_e32 vcc, v169, v151
	s_waitcnt lgkmcnt(4)
	v_mfma_f32_16x16x32_bf16 v[104:107], v[84:87], v[8:11], v[104:107]
	v_cmp_gt_i32_e64 s[2:3], v169, v3
	v_cndmask_b32_e64 v117, 0, v26, s[22:23]
	v_exp_f32_e32 v26, v102
	s_and_b64 s[28:29], vcc, s[2:3]
	s_waitcnt lgkmcnt(3)
	v_mfma_f32_16x16x32_bf16 v[108:111], v[80:83], v[4:7], v[28:31]
	v_cmp_le_i32_e32 vcc, v168, v151
	v_cndmask_b32_e64 v118, 0, v26, s[26:27]
	v_exp_f32_e32 v26, v103
	s_waitcnt lgkmcnt(1)
	v_mfma_f32_16x16x32_bf16 v[112:115], v[72:75], v[4:7], v[28:31]
	v_cmp_gt_i32_e64 s[2:3], v168, v3
	s_and_b64 s[30:31], vcc, s[2:3]
	v_cmp_le_i32_e32 vcc, v167, v151
	v_cndmask_b32_e64 v30, 0, v26, s[28:29]
	v_exp_f32_e32 v26, v104
	v_cmp_gt_i32_e64 s[2:3], v167, v3
	s_and_b64 s[8:9], vcc, s[2:3]
	v_cmp_le_i32_e32 vcc, v166, v151
	v_cndmask_b32_e64 v31, 0, v26, s[30:31]
	v_exp_f32_e32 v26, v105
	v_cmp_gt_i32_e64 s[2:3], v166, v3
	s_and_b64 s[12:13], vcc, s[2:3]
	v_mfma_f32_16x16x32_bf16 v[108:111], v[76:79], v[8:11], v[108:111]
	v_cndmask_b32_e64 v104, 0, v26, s[8:9]
	v_exp_f32_e32 v26, v106
	v_cmp_le_i32_e32 vcc, v165, v151
	v_cmp_gt_i32_e64 s[2:3], v165, v3
	s_and_b64 s[14:15], vcc, s[2:3]
	v_cndmask_b32_e64 v105, 0, v26, s[12:13]
	v_exp_f32_e32 v26, v107
	v_cmp_le_i32_e32 vcc, v164, v151
	v_cmp_gt_i32_e64 s[2:3], v164, v3
	s_and_b64 s[16:17], vcc, s[2:3]
	v_cndmask_b32_e64 v106, 0, v26, s[14:15]
	v_exp_f32_e32 v26, v108
	v_cmp_le_i32_e32 vcc, v163, v151
	v_cmp_gt_i32_e64 s[2:3], v163, v3
	v_exp_f32_e32 v25, v100
	v_cndmask_b32_e64 v107, 0, v26, s[16:17]
	v_exp_f32_e32 v26, v109
	s_and_b64 s[10:11], vcc, s[2:3]
	v_cmp_le_i32_e32 vcc, v162, v151
	v_cmp_gt_i32_e64 s[2:3], v162, v3
	v_cndmask_b32_e64 v108, 0, v26, s[10:11]
	v_exp_f32_e32 v26, v110
	v_cndmask_b32_e64 v116, 0, v25, s[24:25]
	s_and_b64 vcc, vcc, s[2:3]
	v_add_f32_e32 v25, 0, v116
	s_waitcnt lgkmcnt(0)
	v_mfma_f32_16x16x32_bf16 v[100:103], v[68:71], v[8:11], v[112:115]
	v_cndmask_b32_e32 v109, 0, v26, vcc
	v_exp_f32_e32 v26, v111
	v_add_f32_e32 v25, v117, v25
	v_add_f32_e32 v25, v118, v25
	v_cmp_le_i32_e64 s[2:3], v161, v151
	v_cmp_gt_i32_e64 s[4:5], v161, v3
	v_add_f32_e32 v25, v30, v25
	s_and_b64 s[4:5], s[2:3], s[4:5]
	v_add_f32_e32 v25, v31, v25
	v_cndmask_b32_e64 v110, 0, v26, s[4:5]
	v_exp_f32_e32 v26, v100
	v_add_f32_e32 v25, v104, v25
	v_add_f32_e32 v25, v105, v25
	v_cmp_le_i32_e64 s[2:3], v160, v151
	v_cmp_gt_i32_e64 s[6:7], v160, v3
	v_add_f32_e32 v25, v106, v25
	s_and_b64 s[6:7], s[2:3], s[6:7]
	v_add_f32_e32 v25, v107, v25
	v_cndmask_b32_e64 v100, 0, v26, s[6:7]
	v_exp_f32_e32 v26, v101
	v_add_f32_e32 v25, v108, v25
	v_add_f32_e32 v25, v109, v25
	v_cmp_le_i32_e64 s[2:3], v159, v151
	v_cmp_gt_i32_e64 s[18:19], v159, v3
	v_add_f32_e32 v25, v110, v25
	s_and_b64 s[2:3], s[2:3], s[18:19]
	v_add_f32_e32 v25, v100, v25
	v_cndmask_b32_e64 v101, 0, v26, s[2:3]
	v_add_f32_e32 v29, v101, v25
	v_mov_b32_e32 v25, v24
	v_mov_b32_e32 v26, v24
	v_mov_b32_e32 v27, v24
	v_exp_f32_e32 v102, v102
	v_cmp_le_i32_e64 s[18:19], v135, v151
	v_mfma_f32_16x16x32_bf16 v[96:99], v[96:99], v[12:15], v[24:27]
	v_cmp_gt_i32_e64 s[20:21], v135, v3
	s_and_b64 s[18:19], s[18:19], s[20:21]
	v_cmp_le_i32_e64 s[20:21], v156, v151
	v_mfma_f32_16x16x32_bf16 v[88:91], v[88:91], v[12:15], v[24:27]
	v_cmp_gt_i32_e64 s[34:35], v156, v3
	s_and_b64 s[20:21], s[20:21], s[34:35]
	v_mfma_f32_16x16x32_bf16 v[92:95], v[92:95], v[16:19], v[96:99]
	v_mfma_f32_16x16x32_bf16 v[84:87], v[84:87], v[16:19], v[88:91]
	s_nop 1
	v_exp_f32_e32 v97, v103
	v_cndmask_b32_e64 v96, 0, v102, s[18:19]
	v_add_f32_e32 v29, v96, v29
	v_mfma_f32_16x16x32_bf16 v[72:75], v[72:75], v[12:15], v[24:27]
	v_cndmask_b32_e64 v97, 0, v97, s[20:21]
	v_add_f32_e32 v29, v97, v29
	v_cvt_pk_bf16_f32 v89, v118, v30
	v_mfma_f32_16x16x32_bf16 v[80:83], v[80:83], v[12:15], v[24:27]
	v_cvt_pk_bf16_f32 v90, v31, v104
	v_exp_f32_e32 v30, v94
	v_exp_f32_e32 v31, v95
	v_exp_f32_e32 v25, v92
	v_exp_f32_e32 v27, v93
	v_mfma_f32_16x16x32_bf16 v[68:71], v[68:71], v[16:19], v[72:75]
	v_cvt_pk_bf16_f32 v88, v116, v117
	v_cndmask_b32_e64 v25, 0, v25, s[24:25]
	v_cndmask_b32_e64 v27, 0, v27, s[22:23]
	v_exp_f32_e32 v72, v84
	v_exp_f32_e32 v84, v85
	v_mfma_f32_16x16x32_bf16 v[76:79], v[76:79], v[16:19], v[80:83]
	v_add_f32_e32 v26, 0, v25
	v_exp_f32_e32 v85, v86
	v_cndmask_b32_e64 v99, 0, v84, s[8:9]
	v_cvt_pk_bf16_f32 v83, v96, v97
	v_add3_u32 v97, s74, v134, v132
	v_cvt_pk_bf16_f32 v84, v25, v27
	v_add_u32_e32 v25, 0x2800, v97
	s_nop 0
	v_exp_f32_e32 v76, v76
	v_add_u32_e32 v98, 0x2000, v97
	ds_read_b64 v[92:93], v25 offset:1280
	ds_read_b64 v[94:95], v25 offset:1312
	v_cndmask_b32_e64 v96, 0, v72, s[30:31]
	ds_read_b64 v[72:73], v98 offset:1024
	ds_read_b64 v[74:75], v98 offset:1056
	v_exp_f32_e32 v86, v87
	v_cndmask_b32_e64 v118, 0, v76, s[16:17]
	v_exp_f32_e32 v76, v77
	v_cndmask_b32_e64 v30, 0, v30, s[26:27]
	v_cndmask_b32_e64 v31, 0, v31, s[28:29]
	v_cndmask_b32_e64 v116, 0, v85, s[12:13]
	v_cndmask_b32_e64 v117, 0, v86, s[14:15]
	v_cvt_pk_bf16_f32 v91, v105, v106
	v_cvt_pk_bf16_f32 v85, v30, v31
	v_cvt_pk_bf16_f32 v86, v96, v99
	v_cvt_pk_bf16_f32 v87, v116, v117
	v_cndmask_b32_e64 v119, 0, v76, s[10:11]
	v_add3_u32 v76, s74, v133, v132
	v_add_u32_e32 v97, 0x3000, v97
	s_waitcnt lgkmcnt(1)
; DI f32x4 mfma16(bf16x8 a, bf16x8 b, f32x4 c) { return __builtin_amdgcn_mfma_f32_16x16x32_bf16(a, b, c, 0, 0, 0); }
; template <int MODE, bool MASKED, class MaskF>
; DI void flash_tile(const u16* sK, const u16* sV, const bf16x8 (&qf)[2][2], f32x4 (&O)[2][4], float (&m)[2], float (&l)[2],
;                    float (&ps)[4][4], MaskF ok, bool sel, int lane) {
;     ...
;       l[qt] += rs;
;     ...
;   if (MODE != 0) {
; #pragma unroll
;     for (int ks2 = 0; ks2 < 2; ++ks2) {
; #pragma unroll
;       for (int dt = 0; dt < 4; ++dt) {
;         union { uint2 h[2]; bf16x8 v; } vf;
;         vf.h[0] = *(const uint2*)(sV + (16 * dt + l15) * 72 + 32 * ks2 + 4 * lg);
;         vf.h[1] = *(const uint2*)(sV + (16 * dt + l15) * 72 + 32 * ks2 + 16 + 4 * lg);
;         O[0][dt] = mfma16(vf.v, pf[0][ks2].v, O[0][dt]);
;         O[1][dt] = mfma16(vf.v, pf[1][ks2].v, O[1][dt]);
;       }
;     }
	v_mfma_f32_16x16x32_bf16 v[52:55], v[92:95], v[88:91], v[52:55]
	v_cvt_pk_bf16_f32 v82, v100, v101
	v_exp_f32_e32 v100, v78
	v_exp_f32_e32 v101, v79
	v_mfma_f32_16x16x32_bf16 v[56:59], v[92:95], v[84:87], v[56:59]
	v_add_u32_e32 v92, 0x2000, v76
	ds_read_b64 v[76:77], v92 offset:1024
	ds_read_b64 v[78:79], v92 offset:1056
	v_cvt_pk_bf16_f32 v80, v107, v108
	s_waitcnt lgkmcnt(1)
	v_mfma_f32_16x16x32_bf16 v[60:63], v[72:75], v[88:91], v[60:63]
	v_cvt_pk_bf16_f32 v81, v109, v110
	v_exp_f32_e32 v68, v68
	v_cndmask_b32_e32 v93, 0, v100, vcc
	v_mfma_f32_16x16x32_bf16 v[64:67], v[72:75], v[84:87], v[64:67]
	ds_read_b64 v[72:73], v97 offset:1536
	ds_read_b64 v[74:75], v97 offset:1568
	v_cndmask_b32_e64 v95, 0, v68, s[6:7]
	v_exp_f32_e32 v68, v69
	s_waitcnt lgkmcnt(0)
	v_mfma_f32_16x16x32_bf16 v[44:47], v[72:75], v[88:91], v[44:47]
	v_exp_f32_e32 v69, v70
	v_exp_f32_e32 v70, v71
	v_cndmask_b32_e64 v94, 0, v101, s[4:5]
	v_mfma_f32_16x16x32_bf16 v[48:51], v[72:75], v[84:87], v[48:51]
	ds_read_b64 v[72:73], v98 offset:1088
	ds_read_b64 v[74:75], v98 offset:1120
	v_add_f32_e32 v29, v158, v29
	v_mfma_f32_16x16x32_bf16 v[36:39], v[76:79], v[88:91], v[36:39]
	v_cndmask_b32_e64 v88, 0, v68, s[2:3]
	v_cndmask_b32_e64 v89, 0, v69, s[18:19]
	v_cvt_pk_bf16_f32 v68, v118, v119
	v_mfma_f32_16x16x32_bf16 v[40:43], v[76:79], v[84:87], v[40:43]
	ds_read_b64 v[76:77], v25 offset:1344
	ds_read_b64 v[78:79], v25 offset:1376
	v_add_f32_e32 v25, v27, v26
	v_add_f32_e32 v25, v30, v25
	v_add_f32_e32 v25, v31, v25
	s_waitcnt lgkmcnt(1)
	v_mfma_f32_16x16x32_bf16 v[104:107], v[72:75], v[80:83], v[60:63]
	v_add_f32_e32 v25, v96, v25
	v_add_f32_e32 v25, v99, v25
	v_add_f32_e32 v25, v116, v25
	ds_read_b64 v[60:61], v97 offset:1600
	ds_read_b64 v[62:63], v97 offset:1632
	s_waitcnt lgkmcnt(1)
	v_mfma_f32_16x16x32_bf16 v[112:115], v[76:79], v[80:83], v[52:55]
	v_add_f32_e32 v25, v117, v25
	v_add_f32_e32 v25, v118, v25
	v_add_f32_e32 v25, v119, v25
	ds_read_b64 v[52:53], v92 offset:1088
	ds_read_b64 v[54:55], v92 offset:1120
	v_add_f32_e32 v25, v93, v25
	v_cndmask_b32_e64 v84, 0, v70, s[20:21]
	v_add_f32_e32 v25, v94, v25
	v_cvt_pk_bf16_f32 v69, v93, v94
	v_cvt_pk_bf16_f32 v70, v95, v88
	v_cvt_pk_bf16_f32 v71, v89, v84
	v_add_f32_e32 v25, v95, v25
	s_waitcnt lgkmcnt(1)
	v_mfma_f32_16x16x32_bf16 v[120:123], v[60:63], v[80:83], v[44:47]
	v_add_f32_e32 v25, v88, v25
	v_add_f32_e32 v25, v89, v25
	v_add_f32_e32 v25, v84, v25
	v_mfma_f32_16x16x32_bf16 v[100:103], v[72:75], v[68:71], v[64:67]
	v_add_f32_e32 v26, v157, v25
	v_mov_b32_e32 v25, v28
	v_mov_b32_e32 v27, v24
	v_mfma_f32_16x16x32_bf16 v[108:111], v[76:79], v[68:71], v[56:59]
	v_mfma_f32_16x16x32_bf16 v[116:119], v[60:63], v[68:71], v[48:51]
	s_waitcnt lgkmcnt(0)
	v_mfma_f32_16x16x32_bf16 v[128:131], v[52:55], v[80:83], v[36:39]
	v_mfma_f32_16x16x32_bf16 v[124:127], v[52:55], v[68:71], v[40:43]
